# P10 + P4/P6/P12/P0-rms row loops rewritten (batched rows, prefetch, DPP reductions) + attn_sample rewritten (loads up front, row-major V + ds_read_b64_tr_b16)
# speedup vs baseline: 1.0317x; 1.0134x over previous
.LBB0_90:
	v_writelane_b32 v254, s60, 25
	s_nop 1
	v_writelane_b32 v254, s61, 26
	s_or_b64 exec, exec, s[12:13]
	s_lshl_b32 s1, s2, 3
	s_lshl_b32 s0, s96, 3
	v_mov_b32_e32 v1, v198
	v_writelane_b32 v254, s0, 27
	s_add_u32 s88, s94, 0x2102800
	v_ashrrev_i32_e32 v2, 6, v1
	v_writelane_b32 v254, s1, 28
	v_add_u32_e32 v6, s1, v2
	s_movk_i32 s0, 0x4400
	s_addc_u32 s89, s95, 0
	v_writelane_b32 v254, s1, 29
	v_cmp_gt_i32_e32 vcc, s0, v6
	v_mbcnt_lo_u32_b32 v199, -1, 0
	s_and_saveexec_b64 s[0:1], vcc
	s_cbranch_execz .LBB0_95
	s_waitcnt lgkmcnt(0)
	v_readlane_b32 s4, v254, 27
	s_mov_b32 s18, 0x800000
	s_movk_i32 s19, 0x43ff
	s_ashr_i32 s5, s4, 31
	s_nop 0
	v_writelane_b32 v254, s5, 28
	v_and_b32_e32 v0, 63, v198
	v_lshlrev_b32_e32 v1, 3, v0
	v_lshlrev_b32_e32 v2, 4, v0
	v_mov_b32_e32 v3, 0x358637bd
	s_mov_b32 s76, s50
	s_mov_b32 s77, s51
	global_load_dwordx4 v[4:7], v2, s[76:77]
	global_load_dwordx4 v[8:11], v2, s[76:77] offset:1024
	global_load_dwordx4 v[12:15], v2, s[76:77] offset:2048
	global_load_dwordx4 v[16:19], v2, s[76:77] offset:3072
	s_add_u32 s70, s94, 0x2102800
	s_addc_u32 s71, s95, 0
	v_lshrrev_b32_e32 v104, 6, v198
	s_lshl_b32 s26, s96, 3
	v_readfirstlane_b32 s7, v104
	s_mul_i32 s32, s26, 2
	s_nop 3
	s_lshl_b32 s81, s2, 3
	s_add_u32 s7, s7, s81
	s_add_u32 s61, s7, s26
	s_cmp_lt_u32 s61, 0x4400
	s_cselect_b32 s61, s61, s7
	s_lshl_b32 s81, s7, 11
	v_add_u32_e32 v100, s81, v1
	s_cmp_lt_u32 s7, 0x4000
	s_cselect_b32 s10, s36, s38
	s_cselect_b32 s11, s37, s39
	s_cselect_b32 s81, 0, 0x4000
	s_sub_u32 s81, s7, s81
	s_lshl_b32 s81, s81, 12
	s_add_u32 s10, s10, s81
	s_addc_u32 s11, s11, 0
	s_lshl_b32 s81, s61, 11
	v_add_u32_e32 v101, s81, v1
	s_cmp_lt_u32 s61, 0x4000
	s_cselect_b32 s24, s36, s38
	s_cselect_b32 s25, s37, s39
	s_cselect_b32 s81, 0, 0x4000
	s_sub_u32 s81, s61, s81
	s_lshl_b32 s81, s81, 12
	s_add_u32 s24, s24, s81
	s_addc_u32 s25, s25, 0
	global_load_dwordx4 v[20:23], v2, s[10:11]
	global_load_dwordx4 v[24:27], v2, s[10:11] offset:1024
	global_load_dwordx4 v[28:31], v2, s[10:11] offset:2048
	global_load_dwordx4 v[32:35], v2, s[10:11] offset:3072
	global_load_dwordx4 v[36:39], v2, s[24:25]
	global_load_dwordx4 v[40:43], v2, s[24:25] offset:1024
	global_load_dwordx4 v[44:47], v2, s[24:25] offset:2048
	global_load_dwordx4 v[48:51], v2, s[24:25] offset:3072
	s_waitcnt vmcnt(0)
.Lrow_p0r_top:
	v_mov_b64_e32 v[52:53], v[20:21]
	v_mov_b64_e32 v[54:55], v[22:23]
	v_mov_b64_e32 v[56:57], v[24:25]
	v_mov_b64_e32 v[58:59], v[26:27]
	v_mov_b64_e32 v[60:61], v[28:29]
	v_mov_b64_e32 v[62:63], v[30:31]
	v_mov_b64_e32 v[64:65], v[32:33]
	v_mov_b64_e32 v[66:67], v[34:35]
	v_mov_b32_e32 v102, v100
	v_mov_b64_e32 v[68:69], v[36:37]
	v_mov_b64_e32 v[70:71], v[38:39]
	v_mov_b64_e32 v[72:73], v[40:41]
	v_mov_b64_e32 v[74:75], v[42:43]
	v_mov_b64_e32 v[76:77], v[44:45]
	v_mov_b64_e32 v[78:79], v[46:47]
	v_mov_b64_e32 v[80:81], v[48:49]
	v_mov_b64_e32 v[82:83], v[50:51]
	v_mov_b32_e32 v103, v101
	s_add_u32 s49, s7, s32
	s_cmp_lt_u32 s49, 0x4400
	s_cbranch_scc0 .Lrow_p0r_noload
	s_add_u32 s61, s49, s26
	s_cmp_lt_u32 s61, 0x4400
	s_cselect_b32 s61, s61, s49
	s_lshl_b32 s81, s49, 11
	v_add_u32_e32 v100, s81, v1
	s_cmp_lt_u32 s49, 0x4000
	s_cselect_b32 s10, s36, s38
	s_cselect_b32 s11, s37, s39
	s_cselect_b32 s81, 0, 0x4000
	s_sub_u32 s81, s49, s81
	s_lshl_b32 s81, s81, 12
	s_add_u32 s10, s10, s81
	s_addc_u32 s11, s11, 0
	s_lshl_b32 s81, s61, 11
	v_add_u32_e32 v101, s81, v1
	s_cmp_lt_u32 s61, 0x4000
	s_cselect_b32 s24, s36, s38
	s_cselect_b32 s25, s37, s39
	s_cselect_b32 s81, 0, 0x4000
	s_sub_u32 s81, s61, s81
	s_lshl_b32 s81, s81, 12
	s_add_u32 s24, s24, s81
	s_addc_u32 s25, s25, 0
	global_load_dwordx4 v[20:23], v2, s[10:11]
	global_load_dwordx4 v[24:27], v2, s[10:11] offset:1024
	global_load_dwordx4 v[28:31], v2, s[10:11] offset:2048
	global_load_dwordx4 v[32:35], v2, s[10:11] offset:3072
	global_load_dwordx4 v[36:39], v2, s[24:25]
	global_load_dwordx4 v[40:43], v2, s[24:25] offset:1024
	global_load_dwordx4 v[44:47], v2, s[24:25] offset:2048
	global_load_dwordx4 v[48:51], v2, s[24:25] offset:3072
.Lrow_p0r_noload:
	v_mul_f32_e32 v104, v52, v52
	v_mul_f32_e32 v106, v53, v53
	v_fmac_f32_e32 v104, v54, v54
	v_fmac_f32_e32 v106, v55, v55
	v_fmac_f32_e32 v104, v56, v56
	v_fmac_f32_e32 v106, v57, v57
	v_fmac_f32_e32 v104, v58, v58
	v_fmac_f32_e32 v106, v59, v59
	v_fmac_f32_e32 v104, v60, v60
	v_fmac_f32_e32 v106, v61, v61
	v_fmac_f32_e32 v104, v62, v62
	v_fmac_f32_e32 v106, v63, v63
	v_fmac_f32_e32 v104, v64, v64
	v_fmac_f32_e32 v106, v65, v65
	v_fmac_f32_e32 v104, v66, v66
	v_fmac_f32_e32 v106, v67, v67
	v_add_f32_e32 v104, v104, v106
	v_mul_f32_e32 v105, v68, v68
	v_mul_f32_e32 v107, v69, v69
	v_fmac_f32_e32 v105, v70, v70
	v_fmac_f32_e32 v107, v71, v71
	v_fmac_f32_e32 v105, v72, v72
	v_fmac_f32_e32 v107, v73, v73
	v_fmac_f32_e32 v105, v74, v74
	v_fmac_f32_e32 v107, v75, v75
	v_fmac_f32_e32 v105, v76, v76
	v_fmac_f32_e32 v107, v77, v77
	v_fmac_f32_e32 v105, v78, v78
	v_fmac_f32_e32 v107, v79, v79
	v_fmac_f32_e32 v105, v80, v80
	v_fmac_f32_e32 v107, v81, v81
	v_fmac_f32_e32 v105, v82, v82
	v_fmac_f32_e32 v107, v83, v83
	v_add_f32_e32 v105, v105, v107
	s_nop 1
	v_add_f32_dpp v104, v104, v104 quad_perm:[1,0,3,2] row_mask:0xf bank_mask:0xf
	v_add_f32_dpp v105, v105, v105 quad_perm:[1,0,3,2] row_mask:0xf bank_mask:0xf
	s_nop 1
	v_add_f32_dpp v104, v104, v104 quad_perm:[2,3,0,1] row_mask:0xf bank_mask:0xf
	v_add_f32_dpp v105, v105, v105 quad_perm:[2,3,0,1] row_mask:0xf bank_mask:0xf
	s_nop 1
	v_add_f32_dpp v104, v104, v104 row_half_mirror row_mask:0xf bank_mask:0xf
	v_add_f32_dpp v105, v105, v105 row_half_mirror row_mask:0xf bank_mask:0xf
	s_nop 1
	v_add_f32_dpp v104, v104, v104 row_mirror row_mask:0xf bank_mask:0xf
	v_add_f32_dpp v105, v105, v105 row_mirror row_mask:0xf bank_mask:0xf
	s_nop 1
	v_readlane_b32 s82, v104, 0
	v_readlane_b32 s83, v104, 16
	v_readlane_b32 s84, v104, 32
	v_readlane_b32 s85, v104, 48
	s_nop 1
	v_mov_b32_e32 v108, s82
	v_add_f32_e32 v108, s83, v108
	v_add_f32_e32 v108, s84, v108
	v_add_f32_e32 v108, s85, v108
	v_readlane_b32 s82, v105, 0
	v_readlane_b32 s83, v105, 16
	v_readlane_b32 s84, v105, 32
	v_readlane_b32 s85, v105, 48
	s_nop 1
	v_mov_b32_e32 v110, s82
	v_add_f32_e32 v110, s83, v110
	v_add_f32_e32 v110, s84, v110
	v_add_f32_e32 v110, s85, v110
	v_fmamk_f32 v108, v108, 0x3a800000, v3
	v_fmamk_f32 v110, v110, 0x3a800000, v3
	v_rsq_f32_e32 v108, v108
	v_rsq_f32_e32 v110, v110
	s_nop 1
	v_pk_mul_f32 v[52:53], v[52:53], v[108:109] op_sel_hi:[1,0]
	v_pk_mul_f32 v[54:55], v[54:55], v[108:109] op_sel_hi:[1,0]
	v_pk_mul_f32 v[56:57], v[56:57], v[108:109] op_sel_hi:[1,0]
	v_pk_mul_f32 v[58:59], v[58:59], v[108:109] op_sel_hi:[1,0]
	v_pk_mul_f32 v[60:61], v[60:61], v[108:109] op_sel_hi:[1,0]
	v_pk_mul_f32 v[62:63], v[62:63], v[108:109] op_sel_hi:[1,0]
	v_pk_mul_f32 v[64:65], v[64:65], v[108:109] op_sel_hi:[1,0]
	v_pk_mul_f32 v[66:67], v[66:67], v[108:109] op_sel_hi:[1,0]
	v_pk_mul_f32 v[52:53], v[52:53], v[4:5]
	v_pk_mul_f32 v[54:55], v[54:55], v[6:7]
	v_pk_mul_f32 v[56:57], v[56:57], v[8:9]
	v_pk_mul_f32 v[58:59], v[58:59], v[10:11]
	v_pk_mul_f32 v[60:61], v[60:61], v[12:13]
	v_pk_mul_f32 v[62:63], v[62:63], v[14:15]
	v_pk_mul_f32 v[64:65], v[64:65], v[16:17]
	v_pk_mul_f32 v[66:67], v[66:67], v[18:19]
	v_cvt_pk_bf16_f32 v84, v52, v53
	v_cvt_pk_bf16_f32 v85, v54, v55
	v_cvt_pk_bf16_f32 v86, v56, v57
	v_cvt_pk_bf16_f32 v87, v58, v59
	v_cvt_pk_bf16_f32 v88, v60, v61
	v_cvt_pk_bf16_f32 v89, v62, v63
	v_cvt_pk_bf16_f32 v90, v64, v65
	v_cvt_pk_bf16_f32 v91, v66, v67
	global_store_dwordx2 v102, v[84:85], s[70:71]
	global_store_dwordx2 v102, v[86:87], s[70:71] offset:512
	global_store_dwordx2 v102, v[88:89], s[70:71] offset:1024
	global_store_dwordx2 v102, v[90:91], s[70:71] offset:1536
	v_pk_mul_f32 v[68:69], v[68:69], v[110:111] op_sel_hi:[1,0]
	v_pk_mul_f32 v[70:71], v[70:71], v[110:111] op_sel_hi:[1,0]
	v_pk_mul_f32 v[72:73], v[72:73], v[110:111] op_sel_hi:[1,0]
	v_pk_mul_f32 v[74:75], v[74:75], v[110:111] op_sel_hi:[1,0]
	v_pk_mul_f32 v[76:77], v[76:77], v[110:111] op_sel_hi:[1,0]
	v_pk_mul_f32 v[78:79], v[78:79], v[110:111] op_sel_hi:[1,0]
	v_pk_mul_f32 v[80:81], v[80:81], v[110:111] op_sel_hi:[1,0]
	v_pk_mul_f32 v[82:83], v[82:83], v[110:111] op_sel_hi:[1,0]
	v_pk_mul_f32 v[68:69], v[68:69], v[4:5]
	v_pk_mul_f32 v[70:71], v[70:71], v[6:7]
	v_pk_mul_f32 v[72:73], v[72:73], v[8:9]
	v_pk_mul_f32 v[74:75], v[74:75], v[10:11]
	v_pk_mul_f32 v[76:77], v[76:77], v[12:13]
	v_pk_mul_f32 v[78:79], v[78:79], v[14:15]
	v_pk_mul_f32 v[80:81], v[80:81], v[16:17]
	v_pk_mul_f32 v[82:83], v[82:83], v[18:19]
	v_cvt_pk_bf16_f32 v92, v68, v69
	v_cvt_pk_bf16_f32 v93, v70, v71
	v_cvt_pk_bf16_f32 v94, v72, v73
	v_cvt_pk_bf16_f32 v95, v74, v75
	v_cvt_pk_bf16_f32 v96, v76, v77
	v_cvt_pk_bf16_f32 v97, v78, v79
	v_cvt_pk_bf16_f32 v98, v80, v81
	v_cvt_pk_bf16_f32 v99, v82, v83
	global_store_dwordx2 v103, v[92:93], s[70:71]
	global_store_dwordx2 v103, v[94:95], s[70:71] offset:512
	global_store_dwordx2 v103, v[96:97], s[70:71] offset:1024
	global_store_dwordx2 v103, v[98:99], s[70:71] offset:1536
	s_cmp_lt_u32 s49, 0x4400
	s_cbranch_scc0 .Lrow_p0r_done
	s_mov_b32 s7, s49
	s_waitcnt vmcnt(8)
	s_branch .Lrow_p0r_top
.Lrow_p0r_done:
	s_mov_b64 s[6:7], exec
.LBB0_95:
	s_or_b64 exec, exec, s[0:1]
	s_cmp_eq_u64 s[94:95], 0
	s_cbranch_scc0 .LBB0_107
	v_lshrrev_b32_e32 v1, 20, v0
	v_lshrrev_b32_e32 v0, 10, v0
	v_or_b32_e32 v0, v0, v1
	s_movk_i32 s0, 0x3ff
	v_and_or_b32 v0, v0, s0, v198
	v_cmp_eq_u32_e32 vcc, 0, v0
	s_waitcnt lgkmcnt(0)
	s_barrier
	s_and_saveexec_b64 s[0:1], vcc
	s_cbranch_execz .LBB0_106
	buffer_wbl2 sc1
	s_waitcnt vmcnt(0)
	s_load_dwordx2 s[4:5], s[10:11], 0x58
	v_mov_b32_e32 v2, 0
	s_mov_b64 s[6:7], exec
	v_mbcnt_lo_u32_b32 v1, s6, 0
	v_mbcnt_hi_u32_b32 v1, s7, v1
	s_waitcnt lgkmcnt(0)
	global_load_dword v0, v2, s[4:5] offset:40
	v_cmp_eq_u32_e32 vcc, 0, v1
	s_and_saveexec_b64 s[10:11], vcc
	s_cbranch_execz .LBB0_99
	s_bcnt1_i32_b64 s3, s[6:7]
	v_mov_b32_e32 v3, s3
	global_atomic_add v3, v2, v3, s[4:5] offset:32 sc0

.LBB0_659:
	s_add_u32 s0, s94, 0x16402800
	s_addc_u32 s1, s95, 0
	v_writelane_b32 v254, s0, 47
	s_nop 1
	v_writelane_b32 v254, s1, 48
	s_nop 0
	v_readlane_b32 s0, v254, 55
	v_readlane_b32 s1, v254, 56
	s_and_b64 vcc, exec, s[0:1]
	s_cbranch_vccnz .LBB0_684
	s_lshr_b32 s9, s2, 1
	s_and_b32 s10, s2, 1
	s_lshl_b32 s6, s9, 17
	s_lshl_b32 s7, s10, 9
	s_add_u32 s6, s6, s7
	s_add_u32 s60, s40, s6
	s_addc_u32 s61, s41, 0
	s_add_u32 s62, s42, s6
	s_addc_u32 s63, s43, 0
	s_add_u32 s7, s6, 0x44fe000
	s_add_u32 s64, s92, s7
	s_addc_u32 s65, s93, 0
	s_add_u32 s7, s6, 0x54fe000
	s_add_u32 s66, s92, s7
	s_addc_u32 s67, s93, 0
	s_add_u32 s7, s6, 0x451e000
	s_add_u32 s68, s92, s7
	s_addc_u32 s69, s93, 0
	s_add_u32 s7, s6, 0x551e000
	s_add_u32 s70, s92, s7
	s_addc_u32 s71, s93, 0
	v_lshrrev_b32_e32 v0, 4, v198
	v_and_b32_e32 v1, 15, v198
	v_lshlrev_b32_e32 v2, 10, v0
	v_lshl_add_u32 v2, v1, 4, v2
	v_add_u32_e32 v3, 0x8000, v2
	v_add_u32_e32 v4, 0x10000, v2
	v_add_u32_e32 v5, 0x18000, v2
	v_mul_u32_u24_e32 v8, 144, v0
	v_lshl_add_u32 v8, v1, 3, v8
	v_add_u32_e32 v9, 41472, v8
	v_lshrrev_b32_e32 v10, 6, v198
	v_mov_b32_e32 v12, 0
	v_mov_b32_e32 v13, 0
	v_readfirstlane_b32 s8, v10
	global_load_dwordx4 v[16:19], v2, s[60:61]
	global_load_dwordx4 v[20:23], v3, s[60:61]
	global_load_dwordx4 v[24:27], v4, s[60:61]
	global_load_dwordx4 v[28:31], v5, s[60:61]
	global_load_dwordx4 v[32:35], v2, s[62:63]
	global_load_dwordx4 v[36:39], v3, s[62:63]
	global_load_dwordx4 v[40:43], v4, s[62:63]
	global_load_dwordx4 v[44:47], v5, s[62:63]
	global_load_dwordx4 v[48:51], v2, s[60:61] offset:256
	global_load_dwordx4 v[52:55], v3, s[60:61] offset:256
	global_load_dwordx4 v[56:59], v4, s[60:61] offset:256
	global_load_dwordx4 v[60:63], v5, s[60:61] offset:256
	global_load_dwordx4 v[64:67], v2, s[62:63] offset:256
	global_load_dwordx4 v[68:71], v3, s[62:63] offset:256
	global_load_dwordx4 v[72:75], v4, s[62:63] offset:256
	global_load_dwordx4 v[76:79], v5, s[62:63] offset:256
	s_cmp_lt_u32 s8, 2
	s_cbranch_scc0 .Las_noextra_ld
	global_load_dwordx4 v[80:83], v2, s[68:69]
	global_load_dwordx4 v[84:87], v2, s[70:71]
	global_load_dwordx4 v[88:91], v2, s[68:69] offset:256
	global_load_dwordx4 v[92:95], v2, s[70:71] offset:256
.Las_noextra_ld:
	s_barrier
	s_cmp_lt_u32 s8, 4
	s_cselect_b32 s11, 1, 0
	s_cmp_gt_u32 s8, 1
	s_cselect_b32 s15, 1, 0
	s_and_b32 s11, s11, s15
	s_cmp_eq_u32 s11, 1
	s_cbranch_scc0 .Las_nozero
	ds_write_b64 v8, v[12:13] offset:18432
	ds_write_b64 v8, v[12:13] offset:39168
	ds_write_b64 v9, v[12:13] offset:18432
	ds_write_b64 v9, v[12:13] offset:39168
.Las_nozero:
	s_waitcnt vmcnt(15)
	s_cmp_lt_u32 s8, 2
	s_cbranch_scc1 .Las_nost_00
	global_store_dwordx4 v2, v[16:19], s[64:65]
.Las_nost_00:
	v_cvt_pk_bf16_f32 v14, v16, v17
	v_cvt_pk_bf16_f32 v15, v18, v19
	ds_write_b64 v8, v[14:15] offset:0
	s_waitcnt vmcnt(15)
	global_store_dwordx4 v3, v[20:23], s[64:65]
	v_cvt_pk_bf16_f32 v14, v20, v21
	v_cvt_pk_bf16_f32 v15, v22, v23
	ds_write_b64 v8, v[14:15] offset:4608
	s_waitcnt vmcnt(15)
	global_store_dwordx4 v4, v[24:27], s[64:65]
	v_cvt_pk_bf16_f32 v14, v24, v25
	v_cvt_pk_bf16_f32 v15, v26, v27
	ds_write_b64 v8, v[14:15] offset:9216
	s_waitcnt vmcnt(15)
	global_store_dwordx4 v5, v[28:31], s[64:65]
	v_cvt_pk_bf16_f32 v14, v28, v29
	v_cvt_pk_bf16_f32 v15, v30, v31
	ds_write_b64 v8, v[14:15] offset:13824
	s_waitcnt vmcnt(15)
	s_cmp_lt_u32 s8, 2
	s_cbranch_scc1 .Las_nost_01
	global_store_dwordx4 v2, v[32:35], s[66:67]
.Las_nost_01:
	v_cvt_pk_bf16_f32 v14, v32, v33
	v_cvt_pk_bf16_f32 v15, v34, v35
	ds_write_b64 v8, v[14:15] offset:20736
	s_waitcnt vmcnt(15)
	global_store_dwordx4 v3, v[36:39], s[66:67]
	v_cvt_pk_bf16_f32 v14, v36, v37
	v_cvt_pk_bf16_f32 v15, v38, v39
	ds_write_b64 v8, v[14:15] offset:25344
	s_waitcnt vmcnt(15)
	global_store_dwordx4 v4, v[40:43], s[66:67]
	v_cvt_pk_bf16_f32 v14, v40, v41
	v_cvt_pk_bf16_f32 v15, v42, v43
	ds_write_b64 v8, v[14:15] offset:29952
	s_waitcnt vmcnt(15)
	global_store_dwordx4 v5, v[44:47], s[66:67]
	v_cvt_pk_bf16_f32 v14, v44, v45
	v_cvt_pk_bf16_f32 v15, v46, v47
	ds_write_b64 v8, v[14:15] offset:34560
	s_waitcnt vmcnt(15)
	s_cmp_lt_u32 s8, 2
	s_cbranch_scc1 .Las_nost_10
	global_store_dwordx4 v2, v[48:51], s[64:65] offset:256
.Las_nost_10:
	v_cvt_pk_bf16_f32 v14, v48, v49
	v_cvt_pk_bf16_f32 v15, v50, v51
	ds_write_b64 v9, v[14:15] offset:0
	s_waitcnt vmcnt(15)
	global_store_dwordx4 v3, v[52:55], s[64:65] offset:256
	v_cvt_pk_bf16_f32 v14, v52, v53
	v_cvt_pk_bf16_f32 v15, v54, v55
	ds_write_b64 v9, v[14:15] offset:4608
	s_waitcnt vmcnt(15)
	global_store_dwordx4 v4, v[56:59], s[64:65] offset:256
	v_cvt_pk_bf16_f32 v14, v56, v57
	v_cvt_pk_bf16_f32 v15, v58, v59
	ds_write_b64 v9, v[14:15] offset:9216
	s_waitcnt vmcnt(15)
	global_store_dwordx4 v5, v[60:63], s[64:65] offset:256
	v_cvt_pk_bf16_f32 v14, v60, v61
	v_cvt_pk_bf16_f32 v15, v62, v63
	ds_write_b64 v9, v[14:15] offset:13824
	s_waitcnt vmcnt(15)
	s_cmp_lt_u32 s8, 2
	s_cbranch_scc1 .Las_nost_11
	global_store_dwordx4 v2, v[64:67], s[66:67] offset:256
.Las_nost_11:
	v_cvt_pk_bf16_f32 v14, v64, v65
	v_cvt_pk_bf16_f32 v15, v66, v67
	ds_write_b64 v9, v[14:15] offset:20736
	s_waitcnt vmcnt(15)
	global_store_dwordx4 v3, v[68:71], s[66:67] offset:256
	v_cvt_pk_bf16_f32 v14, v68, v69
	v_cvt_pk_bf16_f32 v15, v70, v71
	ds_write_b64 v9, v[14:15] offset:25344
	s_waitcnt vmcnt(15)
	global_store_dwordx4 v4, v[72:75], s[66:67] offset:256
	v_cvt_pk_bf16_f32 v14, v72, v73
	v_cvt_pk_bf16_f32 v15, v74, v75
	ds_write_b64 v9, v[14:15] offset:29952
	s_waitcnt vmcnt(15)
	global_store_dwordx4 v5, v[76:79], s[66:67] offset:256
	v_cvt_pk_bf16_f32 v14, v76, v77
	v_cvt_pk_bf16_f32 v15, v78, v79
	ds_write_b64 v9, v[14:15] offset:34560
	s_cmp_lt_u32 s8, 2
	s_cbranch_scc0 .Las_noextra_st
	s_waitcnt vmcnt(0)
	v_cvt_pk_bf16_f32 v14, v80, v81
	v_cvt_pk_bf16_f32 v15, v82, v83
	ds_write_b64 v8, v[14:15] offset:18432
	v_cvt_pk_bf16_f32 v14, v84, v85
	v_cvt_pk_bf16_f32 v15, v86, v87
	ds_write_b64 v8, v[14:15] offset:39168
	v_cvt_pk_bf16_f32 v14, v88, v89
	v_cvt_pk_bf16_f32 v15, v90, v91
	ds_write_b64 v9, v[14:15] offset:18432
	v_cvt_pk_bf16_f32 v14, v92, v93
	v_cvt_pk_bf16_f32 v15, v94, v95
	ds_write_b64 v9, v[14:15] offset:39168
.Las_noextra_st:
	s_waitcnt lgkmcnt(0)
	s_barrier
	s_cmp_lt_u32 s8, 4
	s_cbranch_scc0 .Las_done
	s_lshr_b32 s6, s8, 1
	s_and_b32 s7, s8, 1
	s_lshl_b32 s15, s10, 1
	s_add_u32 s15, s15, s6
	s_lshl_b32 s15, s15, 2
	s_lshl_b32 s16, s7, 1
	s_add_u32 s15, s15, s16
	s_mul_i32 s17, s6, 41472
	s_lshl_b32 s16, s9, 14
	s_add_u32 s16, s16, 0x2000000
	s_lshl_b32 s24, s15, 7
	s_add_u32 s16, s16, s24
	s_add_u32 s24, s16, 0x1a802800
	s_add_u32 s72, s94, s24
	s_addc_u32 s73, s95, 0
	s_add_u32 s24, s16, 0x1ec02800
	s_add_u32 s74, s94, s24
	s_addc_u32 s75, s95, 0
	s_add_u32 s24, s16, 0x16402800
	s_add_u32 s76, s94, s24
	s_addc_u32 s77, s95, 0
	v_readlane_b32 s78, v254, 9
	v_readlane_b32 s79, v254, 10
	s_lshl_b32 s24, s15, 2
	s_nop 1
	s_add_u32 s78, s78, s24
	s_addc_u32 s79, s79, 0
	v_and_b32_e32 v100, 15, v198
	v_bfe_u32 v101, v198, 4, 2
	v_and_b32_e32 v102, 7, v198
	v_bfe_u32 v103, v198, 3, 1
	v_lshlrev_b32_e32 v104, 11, v102
	v_lshl_add_u32 v104, v103, 7, v104
	v_lshl_add_u32 v105, v101, 3, v104
	v_lshl_add_u32 v104, v101, 4, v104
	v_lshlrev_b32_e32 v111, 2, v103
	global_load_dword v112, v111, s[78:79]
	global_load_dwordx4 v[116:119], v104, s[72:73]
	global_load_dwordx4 v[120:123], v104, s[72:73] offset:64
	global_load_dwordx2 v[124:125], v105, s[74:75]
	global_load_dwordx2 v[126:127], v105, s[74:75] offset:32
	global_load_dwordx2 v[128:129], v105, s[74:75] offset:64
	global_load_dwordx2 v[130:131], v105, s[74:75] offset:96
	v_mul_u32_u24_e32 v106, 144, v100
	v_lshl_add_u32 v106, v101, 4, v106
	v_add_u32_e32 v106, s17, v106
	v_lshrrev_b32_e32 v107, 2, v100
	v_lshl_add_u32 v107, v101, 2, v107
	v_mul_u32_u24_e32 v107, 144, v107
	v_and_b32_e32 v113, 3, v100
	v_lshl_add_u32 v107, v113, 3, v107
	v_add_u32_e32 v107, s17, v107
	v_add_u32_e32 v107, 20736, v107
	v_lshlrev_b32_e32 v113, 2, v101
	v_sub_u32_e32 v108, v102, v113
	v_and_b32_e32 v113, 63, v198
	v_xor_b32_e32 v109, 16, v113
	v_lshlrev_b32_e32 v109, 2, v109
	v_xor_b32_e32 v110, 32, v113
	v_lshlrev_b32_e32 v110, 2, v110
	ds_read_b128 v[52:55], v106 offset:0
	ds_read_b128 v[56:59], v106 offset:64
	ds_read_b128 v[60:63], v106 offset:2304
	s_waitcnt vmcnt(4)
	ds_read_b128 v[64:67], v106 offset:2368
	s_waitcnt lgkmcnt(3)
	v_mfma_f32_16x16x32_bf16 v[16:19], v[52:55], v[116:119], 0
	ds_read_b128 v[52:55], v106 offset:4608
	s_waitcnt lgkmcnt(3)
	v_mfma_f32_16x16x32_bf16 v[16:19], v[56:59], v[120:123], v[16:19]
	ds_read_b128 v[56:59], v106 offset:4672
	s_waitcnt lgkmcnt(3)
	v_mfma_f32_16x16x32_bf16 v[20:23], v[60:63], v[116:119], 0
	ds_read_b128 v[60:63], v106 offset:6912
	s_waitcnt lgkmcnt(3)
	v_mfma_f32_16x16x32_bf16 v[20:23], v[64:67], v[120:123], v[20:23]
	ds_read_b128 v[64:67], v106 offset:6976
	s_waitcnt lgkmcnt(3)
	v_mfma_f32_16x16x32_bf16 v[24:27], v[52:55], v[116:119], 0
	ds_read_b128 v[52:55], v106 offset:9216
	s_waitcnt lgkmcnt(3)
	v_mfma_f32_16x16x32_bf16 v[24:27], v[56:59], v[120:123], v[24:27]
	ds_read_b128 v[56:59], v106 offset:9280
	s_waitcnt lgkmcnt(3)
	v_mfma_f32_16x16x32_bf16 v[28:31], v[60:63], v[116:119], 0
	ds_read_b128 v[60:63], v106 offset:11520
	s_waitcnt lgkmcnt(3)
	v_mfma_f32_16x16x32_bf16 v[28:31], v[64:67], v[120:123], v[28:31]
	ds_read_b128 v[64:67], v106 offset:11584
	s_waitcnt lgkmcnt(3)
	v_mfma_f32_16x16x32_bf16 v[32:35], v[52:55], v[116:119], 0
	ds_read_b128 v[52:55], v106 offset:13824
	s_waitcnt lgkmcnt(3)
	v_mfma_f32_16x16x32_bf16 v[32:35], v[56:59], v[120:123], v[32:35]
	ds_read_b128 v[56:59], v106 offset:13888
	s_waitcnt lgkmcnt(3)
	v_mfma_f32_16x16x32_bf16 v[36:39], v[60:63], v[116:119], 0
	ds_read_b128 v[60:63], v106 offset:16128
	s_waitcnt lgkmcnt(3)
	v_mfma_f32_16x16x32_bf16 v[36:39], v[64:67], v[120:123], v[36:39]
	ds_read_b128 v[64:67], v106 offset:16192
	s_waitcnt lgkmcnt(3)
	v_mfma_f32_16x16x32_bf16 v[40:43], v[52:55], v[116:119], 0
	ds_read_b128 v[52:55], v106 offset:18432
	s_waitcnt lgkmcnt(3)
	v_mfma_f32_16x16x32_bf16 v[40:43], v[56:59], v[120:123], v[40:43]
	ds_read_b128 v[56:59], v106 offset:18496
	s_waitcnt lgkmcnt(3)
	v_mfma_f32_16x16x32_bf16 v[44:47], v[60:63], v[116:119], 0
	s_waitcnt lgkmcnt(2)
	v_mfma_f32_16x16x32_bf16 v[44:47], v[64:67], v[120:123], v[44:47]
	s_waitcnt lgkmcnt(1)
	v_mfma_f32_16x16x32_bf16 v[48:51], v[52:55], v[116:119], 0
	s_waitcnt lgkmcnt(0)
	v_mfma_f32_16x16x32_bf16 v[48:51], v[56:59], v[120:123], v[48:51]
	s_nop 7
	v_mov_b32_e32 v114, 0xf149f2ca
	v_cmp_gt_i32_e32 vcc, 0, v108
	s_nop 1
	v_cndmask_b32_e32 v16, v114, v16, vcc
	v_cmp_gt_i32_e32 vcc, 1, v108
	s_nop 1
	v_cndmask_b32_e32 v17, v114, v17, vcc
	v_cmp_gt_i32_e32 vcc, 2, v108
	s_nop 1
	v_cndmask_b32_e32 v18, v114, v18, vcc
	v_cmp_gt_i32_e32 vcc, 3, v108
	s_nop 1
	v_cndmask_b32_e32 v19, v114, v19, vcc
	v_cmp_le_i32_e32 vcc, 0, v108
	s_nop 1
	v_cndmask_b32_e32 v48, v114, v48, vcc
	v_cmp_le_i32_e32 vcc, 1, v108
	s_nop 1
	v_cndmask_b32_e32 v49, v114, v49, vcc
	v_cmp_le_i32_e32 vcc, 2, v108
	s_nop 1
	v_cndmask_b32_e32 v50, v114, v50, vcc
	v_cmp_le_i32_e32 vcc, 3, v108
	s_nop 1
	v_cndmask_b32_e32 v51, v114, v51, vcc
	v_max3_f32 v68, v112, v16, v17
	v_max3_f32 v68, v68, v18, v19
	v_max3_f32 v68, v68, v20, v21
	v_max3_f32 v68, v68, v22, v23
	v_max3_f32 v68, v68, v24, v25
	v_max3_f32 v68, v68, v26, v27
	v_max3_f32 v68, v68, v28, v29
	v_max3_f32 v68, v68, v30, v31
	v_max3_f32 v68, v68, v32, v33
	v_max3_f32 v68, v68, v34, v35
	v_max3_f32 v68, v68, v36, v37
	v_max3_f32 v68, v68, v38, v39
	v_max3_f32 v68, v68, v40, v41
	v_max3_f32 v68, v68, v42, v43
	v_max3_f32 v68, v68, v44, v45
	v_max3_f32 v68, v68, v46, v47
	v_max3_f32 v68, v68, v48, v49
	v_max3_f32 v68, v68, v50, v51
	ds_bpermute_b32 v69, v109, v68
	s_waitcnt lgkmcnt(0)
	v_max_f32_e32 v68, v68, v69
	ds_bpermute_b32 v69, v110, v68
	s_waitcnt lgkmcnt(0)
	v_max_f32_e32 v68, v68, v69
	v_sub_f32_e32 v16, v16, v68
	v_mul_f32_e32 v16, 0x3fb8aa3b, v16
	v_exp_f32_e32 v16, v16
	v_sub_f32_e32 v17, v17, v68
	v_mul_f32_e32 v17, 0x3fb8aa3b, v17
	v_exp_f32_e32 v17, v17
	v_sub_f32_e32 v18, v18, v68
	v_mul_f32_e32 v18, 0x3fb8aa3b, v18
	v_exp_f32_e32 v18, v18
	v_sub_f32_e32 v19, v19, v68
	v_mul_f32_e32 v19, 0x3fb8aa3b, v19
	v_exp_f32_e32 v19, v19
	v_sub_f32_e32 v20, v20, v68
	v_mul_f32_e32 v20, 0x3fb8aa3b, v20
	v_exp_f32_e32 v20, v20
	v_sub_f32_e32 v21, v21, v68
	v_mul_f32_e32 v21, 0x3fb8aa3b, v21
	v_exp_f32_e32 v21, v21
	v_sub_f32_e32 v22, v22, v68
	v_mul_f32_e32 v22, 0x3fb8aa3b, v22
	v_exp_f32_e32 v22, v22
	v_sub_f32_e32 v23, v23, v68
	v_mul_f32_e32 v23, 0x3fb8aa3b, v23
	v_exp_f32_e32 v23, v23
	v_sub_f32_e32 v24, v24, v68
	v_mul_f32_e32 v24, 0x3fb8aa3b, v24
	v_exp_f32_e32 v24, v24
	v_sub_f32_e32 v25, v25, v68
	v_mul_f32_e32 v25, 0x3fb8aa3b, v25
	v_exp_f32_e32 v25, v25
	v_sub_f32_e32 v26, v26, v68
	v_mul_f32_e32 v26, 0x3fb8aa3b, v26
	v_exp_f32_e32 v26, v26
	v_sub_f32_e32 v27, v27, v68
	v_mul_f32_e32 v27, 0x3fb8aa3b, v27
	v_exp_f32_e32 v27, v27
	v_sub_f32_e32 v28, v28, v68
	v_mul_f32_e32 v28, 0x3fb8aa3b, v28
	v_exp_f32_e32 v28, v28
	v_sub_f32_e32 v29, v29, v68
	v_mul_f32_e32 v29, 0x3fb8aa3b, v29
	v_exp_f32_e32 v29, v29
	v_sub_f32_e32 v30, v30, v68
	v_mul_f32_e32 v30, 0x3fb8aa3b, v30
	v_exp_f32_e32 v30, v30
	v_sub_f32_e32 v31, v31, v68
	v_mul_f32_e32 v31, 0x3fb8aa3b, v31
	v_exp_f32_e32 v31, v31
	v_sub_f32_e32 v32, v32, v68
	v_mul_f32_e32 v32, 0x3fb8aa3b, v32
	v_exp_f32_e32 v32, v32
	v_sub_f32_e32 v33, v33, v68
	v_mul_f32_e32 v33, 0x3fb8aa3b, v33
	v_exp_f32_e32 v33, v33
	v_sub_f32_e32 v34, v34, v68
	v_mul_f32_e32 v34, 0x3fb8aa3b, v34
	v_exp_f32_e32 v34, v34
	v_sub_f32_e32 v35, v35, v68
	v_mul_f32_e32 v35, 0x3fb8aa3b, v35
	v_exp_f32_e32 v35, v35
	v_sub_f32_e32 v36, v36, v68
	v_mul_f32_e32 v36, 0x3fb8aa3b, v36
	v_exp_f32_e32 v36, v36
	v_sub_f32_e32 v37, v37, v68
	v_mul_f32_e32 v37, 0x3fb8aa3b, v37
	v_exp_f32_e32 v37, v37
	v_sub_f32_e32 v38, v38, v68
	v_mul_f32_e32 v38, 0x3fb8aa3b, v38
	v_exp_f32_e32 v38, v38
	v_sub_f32_e32 v39, v39, v68
	v_mul_f32_e32 v39, 0x3fb8aa3b, v39
	v_exp_f32_e32 v39, v39
	v_sub_f32_e32 v40, v40, v68
	v_mul_f32_e32 v40, 0x3fb8aa3b, v40
	v_exp_f32_e32 v40, v40
	v_sub_f32_e32 v41, v41, v68
	v_mul_f32_e32 v41, 0x3fb8aa3b, v41
	v_exp_f32_e32 v41, v41
	v_sub_f32_e32 v42, v42, v68
	v_mul_f32_e32 v42, 0x3fb8aa3b, v42
	v_exp_f32_e32 v42, v42
	v_sub_f32_e32 v43, v43, v68
	v_mul_f32_e32 v43, 0x3fb8aa3b, v43
	v_exp_f32_e32 v43, v43
	v_sub_f32_e32 v44, v44, v68
	v_mul_f32_e32 v44, 0x3fb8aa3b, v44
	v_exp_f32_e32 v44, v44
	v_sub_f32_e32 v45, v45, v68
	v_mul_f32_e32 v45, 0x3fb8aa3b, v45
	v_exp_f32_e32 v45, v45
	v_sub_f32_e32 v46, v46, v68
	v_mul_f32_e32 v46, 0x3fb8aa3b, v46
	v_exp_f32_e32 v46, v46
	v_sub_f32_e32 v47, v47, v68
	v_mul_f32_e32 v47, 0x3fb8aa3b, v47
	v_exp_f32_e32 v47, v47
	v_sub_f32_e32 v48, v48, v68
	v_mul_f32_e32 v48, 0x3fb8aa3b, v48
	v_exp_f32_e32 v48, v48
	v_sub_f32_e32 v49, v49, v68
	v_mul_f32_e32 v49, 0x3fb8aa3b, v49
	v_exp_f32_e32 v49, v49
	v_sub_f32_e32 v50, v50, v68
	v_mul_f32_e32 v50, 0x3fb8aa3b, v50
	v_exp_f32_e32 v50, v50
	v_sub_f32_e32 v51, v51, v68
	v_mul_f32_e32 v51, 0x3fb8aa3b, v51
	v_exp_f32_e32 v51, v51
	s_nop 0
	v_add_f32_e32 v71, v16, v17
	v_add_f32_e32 v71, v71, v18
	v_add_f32_e32 v71, v71, v19
	v_add_f32_e32 v71, v71, v20
	v_add_f32_e32 v71, v71, v21
	v_add_f32_e32 v71, v71, v22
	v_add_f32_e32 v71, v71, v23
	v_add_f32_e32 v71, v71, v24
	v_add_f32_e32 v71, v71, v25
	v_add_f32_e32 v71, v71, v26
	v_add_f32_e32 v71, v71, v27
	v_add_f32_e32 v71, v71, v28
	v_add_f32_e32 v71, v71, v29
	v_add_f32_e32 v71, v71, v30
	v_add_f32_e32 v71, v71, v31
	v_add_f32_e32 v71, v71, v32
	v_add_f32_e32 v71, v71, v33
	v_add_f32_e32 v71, v71, v34
	v_add_f32_e32 v71, v71, v35
	v_add_f32_e32 v71, v71, v36
	v_add_f32_e32 v71, v71, v37
	v_add_f32_e32 v71, v71, v38
	v_add_f32_e32 v71, v71, v39
	v_add_f32_e32 v71, v71, v40
	v_add_f32_e32 v71, v71, v41
	v_add_f32_e32 v71, v71, v42
	v_add_f32_e32 v71, v71, v43
	v_add_f32_e32 v71, v71, v44
	v_add_f32_e32 v71, v71, v45
	v_add_f32_e32 v71, v71, v46
	v_add_f32_e32 v71, v71, v47
	v_add_f32_e32 v71, v71, v48
	v_add_f32_e32 v71, v71, v49
	v_add_f32_e32 v71, v71, v50
	v_add_f32_e32 v71, v71, v51
	ds_bpermute_b32 v69, v109, v71
	s_waitcnt lgkmcnt(0)
	v_add_f32_e32 v71, v71, v69
	ds_bpermute_b32 v69, v110, v71
	s_waitcnt lgkmcnt(0)
	v_add_f32_e32 v71, v71, v69
	v_sub_f32_e32 v69, v112, v68
	v_mul_f32_e32 v69, 0x3fb8aa3b, v69
	v_exp_f32_e32 v69, v69
	s_nop 0
	v_add_f32_e32 v71, v71, v69
	v_rcp_f32_e32 v72, v71
	s_nop 0
	v_fma_f32 v70, -v71, v72, 1.0
	v_fma_f32 v72, v72, v70, v72
	v_mov_b32_e32 v73, v72
	v_cvt_pk_bf16_f32 v76, v16, v17
	v_cvt_pk_bf16_f32 v77, v18, v19
	v_cvt_pk_bf16_f32 v78, v20, v21
	v_cvt_pk_bf16_f32 v79, v22, v23
	v_cvt_pk_bf16_f32 v80, v24, v25
	v_cvt_pk_bf16_f32 v81, v26, v27
	v_cvt_pk_bf16_f32 v82, v28, v29
	v_cvt_pk_bf16_f32 v83, v30, v31
	v_cvt_pk_bf16_f32 v84, v32, v33
	v_cvt_pk_bf16_f32 v85, v34, v35
	v_cvt_pk_bf16_f32 v86, v36, v37
	v_cvt_pk_bf16_f32 v87, v38, v39
	v_cvt_pk_bf16_f32 v88, v40, v41
	v_cvt_pk_bf16_f32 v89, v42, v43
	v_cvt_pk_bf16_f32 v90, v44, v45
	v_cvt_pk_bf16_f32 v91, v46, v47
	v_cvt_pk_bf16_f32 v92, v48, v49
	v_cvt_pk_bf16_f32 v93, v50, v51
	v_mov_b32_e32 v94, 0
	v_mov_b32_e32 v95, 0
	ds_read_b64_tr_b16 v[16:17], v107 offset:0
	ds_read_b64_tr_b16 v[18:19], v107 offset:2304
	ds_read_b64_tr_b16 v[20:21], v107 offset:32
	ds_read_b64_tr_b16 v[22:23], v107 offset:2336
	ds_read_b64_tr_b16 v[24:25], v107 offset:64
	ds_read_b64_tr_b16 v[26:27], v107 offset:2368
	ds_read_b64_tr_b16 v[28:29], v107 offset:96
	ds_read_b64_tr_b16 v[30:31], v107 offset:2400
	s_waitcnt lgkmcnt(6)
	v_mfma_f32_16x16x32_bf16 v[132:135], v[16:19], v[76:79], 0
	ds_read_b64_tr_b16 v[16:17], v107 offset:4608
	ds_read_b64_tr_b16 v[18:19], v107 offset:6912
	s_waitcnt lgkmcnt(6)
	v_mfma_f32_16x16x32_bf16 v[136:139], v[20:23], v[76:79], 0
	ds_read_b64_tr_b16 v[20:21], v107 offset:4640
	ds_read_b64_tr_b16 v[22:23], v107 offset:6944
	s_waitcnt lgkmcnt(6)
	v_mfma_f32_16x16x32_bf16 v[140:143], v[24:27], v[76:79], 0
	ds_read_b64_tr_b16 v[24:25], v107 offset:4672
	ds_read_b64_tr_b16 v[26:27], v107 offset:6976
	s_waitcnt lgkmcnt(6)
	v_mfma_f32_16x16x32_bf16 v[144:147], v[28:31], v[76:79], 0
	ds_read_b64_tr_b16 v[28:29], v107 offset:4704
	ds_read_b64_tr_b16 v[30:31], v107 offset:7008
	s_waitcnt lgkmcnt(6)
	v_mfma_f32_16x16x32_bf16 v[132:135], v[16:19], v[80:83], v[132:135]
	ds_read_b64_tr_b16 v[16:17], v107 offset:9216
	ds_read_b64_tr_b16 v[18:19], v107 offset:11520
	s_waitcnt lgkmcnt(6)
	v_mfma_f32_16x16x32_bf16 v[136:139], v[20:23], v[80:83], v[136:139]
	ds_read_b64_tr_b16 v[20:21], v107 offset:9248
	ds_read_b64_tr_b16 v[22:23], v107 offset:11552
	s_waitcnt lgkmcnt(6)
	v_mfma_f32_16x16x32_bf16 v[140:143], v[24:27], v[80:83], v[140:143]
	ds_read_b64_tr_b16 v[24:25], v107 offset:9280
	ds_read_b64_tr_b16 v[26:27], v107 offset:11584
	s_waitcnt lgkmcnt(6)
	v_mfma_f32_16x16x32_bf16 v[144:147], v[28:31], v[80:83], v[144:147]
	ds_read_b64_tr_b16 v[28:29], v107 offset:9312
	ds_read_b64_tr_b16 v[30:31], v107 offset:11616
	s_waitcnt lgkmcnt(6)
	v_mfma_f32_16x16x32_bf16 v[132:135], v[16:19], v[84:87], v[132:135]
	ds_read_b64_tr_b16 v[16:17], v107 offset:13824
	ds_read_b64_tr_b16 v[18:19], v107 offset:16128
	s_waitcnt lgkmcnt(6)
	v_mfma_f32_16x16x32_bf16 v[136:139], v[20:23], v[84:87], v[136:139]
	ds_read_b64_tr_b16 v[20:21], v107 offset:13856
	ds_read_b64_tr_b16 v[22:23], v107 offset:16160
	s_waitcnt lgkmcnt(6)
	v_mfma_f32_16x16x32_bf16 v[140:143], v[24:27], v[84:87], v[140:143]
	ds_read_b64_tr_b16 v[24:25], v107 offset:13888
	ds_read_b64_tr_b16 v[26:27], v107 offset:16192
	s_waitcnt lgkmcnt(6)
	v_mfma_f32_16x16x32_bf16 v[144:147], v[28:31], v[84:87], v[144:147]
	ds_read_b64_tr_b16 v[28:29], v107 offset:13920
	ds_read_b64_tr_b16 v[30:31], v107 offset:16224
	s_waitcnt lgkmcnt(6)
	v_mfma_f32_16x16x32_bf16 v[132:135], v[16:19], v[88:91], v[132:135]
	ds_read_b64_tr_b16 v[16:17], v107 offset:18432
	ds_read_b64_tr_b16 v[18:19], v107 offset:18432
	s_waitcnt lgkmcnt(6)
	v_mfma_f32_16x16x32_bf16 v[136:139], v[20:23], v[88:91], v[136:139]
	ds_read_b64_tr_b16 v[20:21], v107 offset:18464
	ds_read_b64_tr_b16 v[22:23], v107 offset:18464
	s_waitcnt lgkmcnt(6)
	v_mfma_f32_16x16x32_bf16 v[140:143], v[24:27], v[88:91], v[140:143]
	ds_read_b64_tr_b16 v[24:25], v107 offset:18496
	ds_read_b64_tr_b16 v[26:27], v107 offset:18496
	s_waitcnt lgkmcnt(6)
	v_mfma_f32_16x16x32_bf16 v[144:147], v[28:31], v[88:91], v[144:147]
	ds_read_b64_tr_b16 v[28:29], v107 offset:18528
	ds_read_b64_tr_b16 v[30:31], v107 offset:18528
	s_waitcnt lgkmcnt(6)
	v_mfma_f32_16x16x32_bf16 v[132:135], v[16:19], v[92:95], v[132:135]
	s_waitcnt lgkmcnt(4)
	v_mfma_f32_16x16x32_bf16 v[136:139], v[20:23], v[92:95], v[136:139]
	s_waitcnt lgkmcnt(2)
	v_mfma_f32_16x16x32_bf16 v[140:143], v[24:27], v[92:95], v[140:143]
	s_waitcnt lgkmcnt(0)
	v_mfma_f32_16x16x32_bf16 v[144:147], v[28:31], v[92:95], v[144:147]
	s_nop 7
	s_waitcnt vmcnt(0)
	v_lshlrev_b32_e32 v52, 16, v124
	v_and_b32_e32 v53, 0xffff0000, v124
	v_lshlrev_b32_e32 v54, 16, v125
	v_and_b32_e32 v55, 0xffff0000, v125
	v_pk_mul_f32 v[132:133], v[132:133], v[72:73]
	v_pk_mul_f32 v[134:135], v[134:135], v[72:73]
	v_pk_mul_f32 v[132:133], v[132:133], v[52:53]
	v_pk_mul_f32 v[134:135], v[134:135], v[54:55]
	v_cvt_pk_bf16_f32 v56, v132, v133
	v_cvt_pk_bf16_f32 v57, v134, v135
	global_store_dwordx2 v105, v[56:57], s[76:77]
	v_lshlrev_b32_e32 v52, 16, v126
	v_and_b32_e32 v53, 0xffff0000, v126
	v_lshlrev_b32_e32 v54, 16, v127
	v_and_b32_e32 v55, 0xffff0000, v127
	v_pk_mul_f32 v[136:137], v[136:137], v[72:73]
	v_pk_mul_f32 v[138:139], v[138:139], v[72:73]
	v_pk_mul_f32 v[136:137], v[136:137], v[52:53]
	v_pk_mul_f32 v[138:139], v[138:139], v[54:55]
	v_cvt_pk_bf16_f32 v56, v136, v137
	v_cvt_pk_bf16_f32 v57, v138, v139
	global_store_dwordx2 v105, v[56:57], s[76:77] offset:32
	v_lshlrev_b32_e32 v52, 16, v128
	v_and_b32_e32 v53, 0xffff0000, v128
	v_lshlrev_b32_e32 v54, 16, v129
	v_and_b32_e32 v55, 0xffff0000, v129
	v_pk_mul_f32 v[140:141], v[140:141], v[72:73]
	v_pk_mul_f32 v[142:143], v[142:143], v[72:73]
	v_pk_mul_f32 v[140:141], v[140:141], v[52:53]
	v_pk_mul_f32 v[142:143], v[142:143], v[54:55]
	v_cvt_pk_bf16_f32 v56, v140, v141
	v_cvt_pk_bf16_f32 v57, v142, v143
	global_store_dwordx2 v105, v[56:57], s[76:77] offset:64
	v_lshlrev_b32_e32 v52, 16, v130
	v_and_b32_e32 v53, 0xffff0000, v130
	v_lshlrev_b32_e32 v54, 16, v131
	v_and_b32_e32 v55, 0xffff0000, v131
	v_pk_mul_f32 v[144:145], v[144:145], v[72:73]
	v_pk_mul_f32 v[146:147], v[146:147], v[72:73]
	v_pk_mul_f32 v[144:145], v[144:145], v[52:53]
	v_pk_mul_f32 v[146:147], v[146:147], v[54:55]
	v_cvt_pk_bf16_f32 v56, v144, v145
	v_cvt_pk_bf16_f32 v57, v146, v147
	global_store_dwordx2 v105, v[56:57], s[76:77] offset:96
.Las_done:
.LBB0_684:
	s_waitcnt vmcnt(0)
	s_barrier
	s_mov_b64 s[0:1], exec
	v_readlane_b32 s6, v254, 3
	v_readlane_b32 s7, v254, 4
	s_and_b64 s[6:7], s[0:1], s[6:7]
	s_xor_b64 s[0:1], s[6:7], s[0:1]
	s_mov_b64 exec, s[6:7]
	s_cbranch_execz .LBB0_737
	s_add_i32 s6, 0, 0x22ff0
	v_mov_b32_e32 v0, s6
	s_waitcnt vmcnt(0) expcnt(0) lgkmcnt(0)
	ds_read_b32 v2, v0
	s_add_i32 s6, 0, 0x22ff4
	v_mov_b32_e32 v0, s6
	ds_read_b32 v0, v0
	s_waitcnt lgkmcnt(1)
	v_cmp_ne_u32_e32 vcc, 0, v2
	s_cbranch_vccnz .LBB0_700
	v_readlane_b32 s6, v254, 0
	s_mul_i32 s24, s97, s6
	s_add_u32 s6, s94, 0x32c02a00
	s_addc_u32 s7, s95, 0
	s_add_u32 s8, s94, 0x32c02c00
	s_addc_u32 s9, s95, 0
	s_add_u32 s10, s94, 0x32c02d00
	s_addc_u32 s11, s95, 0
	s_add_u32 s12, s94, 0x32c02e00
	s_addc_u32 s13, s95, 0
	s_add_u32 s14, s94, 0x32c02f00
	s_addc_u32 s15, s95, 0
	s_add_u32 s16, s94, 0x32c03000
	s_addc_u32 s17, s95, 0
	s_add_u32 s18, s94, 0x32c03100
	s_addc_u32 s19, s95, 0
	s_add_u32 s20, s94, 0x32c03200
	s_addc_u32 s21, s95, 0
	s_add_u32 s22, s94, 0x32c03300
	s_addc_u32 s23, s95, 0
	s_add_u32 s40, s94, 0x32c03400
	s_addc_u32 s41, s95, 0
	s_add_u32 s42, s94, 0x32c03500
	s_addc_u32 s43, s95, 0
	s_add_u32 s58, s94, 0x32c03600
	s_addc_u32 s59, s95, 0
	s_add_u32 s60, s94, 0x32c03700
	s_addc_u32 s61, s95, 0
	s_add_u32 s62, s94, 0x32c03800
	s_addc_u32 s63, s95, 0
	s_add_u32 s64, s94, 0x32c03900
	s_addc_u32 s65, s95, 0
	s_add_u32 s66, s94, 0x32c03a00
	s_addc_u32 s67, s95, 0
	s_add_u32 s68, s94, 0x32c03b00
	s_mul_i32 s24, s24, s96
	s_addc_u32 s69, s95, 0
	s_mov_b32 s25, 1
	v_mov_b32_e32 v16, 0
	s_branch .LBB0_688

.LBB0_811:
	s_or_b64 exec, exec, s[0:1]
	v_mov_b32_e32 v10, v198
	s_waitcnt lgkmcnt(0)
	s_barrier
	v_readlane_b32 s0, v254, 29
	v_ashrrev_i32_e32 v0, 6, v10
	s_nop 0
	v_add_u32_e32 v4, s0, v0
	s_movk_i32 s0, 0x4400
	v_cmp_gt_i32_e32 vcc, s0, v4
	s_and_saveexec_b64 s[0:1], vcc
	v_readlane_b32 s72, v254, 27
	v_readlane_b32 s73, v254, 28
	s_cbranch_execz .LBB0_814
	s_ashr_i32 s73, s72, 31
	s_mov_b32 s14, 0x800000
	s_movk_i32 s18, 0x43ff
	v_and_b32_e32 v0, 63, v198
	v_lshlrev_b32_e32 v1, 3, v0
	v_lshlrev_b32_e32 v2, 4, v0
	v_mov_b32_e32 v3, 0x358637bd
	v_readlane_b32 s76, v254, 5
	v_readlane_b32 s77, v254, 6
	s_nop 4
	global_load_dwordx4 v[4:7], v2, s[76:77]
	global_load_dwordx4 v[8:11], v2, s[76:77] offset:1024
	global_load_dwordx4 v[12:15], v2, s[76:77] offset:2048
	global_load_dwordx4 v[16:19], v2, s[76:77] offset:3072
	s_add_u32 s64, s94, 0x9802800
	s_addc_u32 s65, s95, 0
	s_add_u32 s70, s94, 0x2102800
	s_addc_u32 s71, s95, 0
	v_lshrrev_b32_e32 v152, 6, v198
	s_lshl_b32 s26, s96, 3
	v_readfirstlane_b32 s7, v152
	s_mul_i32 s32, s26, 2
	s_nop 3
	s_lshl_b32 s81, s2, 3
	s_add_u32 s7, s7, s81
	s_add_u32 s61, s7, s26
	s_cmp_lt_u32 s61, 0x4400
	s_cselect_b32 s61, s61, s7
	s_lshl_b32 s81, s7, 11
	v_add_u32_e32 v148, s81, v1
	s_cmp_lt_u32 s7, 0x4000
	s_cselect_b32 s10, s36, s38
	s_cselect_b32 s11, s37, s39
	s_cselect_b32 s81, 0, 0x4000
	s_sub_u32 s81, s7, s81
	s_lshl_b32 s81, s81, 12
	s_add_u32 s10, s10, s81
	s_addc_u32 s11, s11, 0
	s_lshl_b32 s81, s61, 11
	v_add_u32_e32 v149, s81, v1
	s_cmp_lt_u32 s61, 0x4000
	s_cselect_b32 s24, s36, s38
	s_cselect_b32 s25, s37, s39
	s_cselect_b32 s81, 0, 0x4000
	s_sub_u32 s81, s61, s81
	s_lshl_b32 s81, s81, 12
	s_add_u32 s24, s24, s81
	s_addc_u32 s25, s25, 0
	global_load_dwordx2 v[20:21], v148, s[64:65]
	global_load_dwordx2 v[22:23], v148, s[64:65] offset:512
	global_load_dwordx2 v[24:25], v148, s[64:65] offset:1024
	global_load_dwordx2 v[26:27], v148, s[64:65] offset:1536
	global_load_dwordx4 v[28:31], v2, s[10:11]
	global_load_dwordx4 v[32:35], v2, s[10:11] offset:1024
	global_load_dwordx4 v[36:39], v2, s[10:11] offset:2048
	global_load_dwordx4 v[40:43], v2, s[10:11] offset:3072
	global_load_dwordx2 v[44:45], v149, s[64:65]
	global_load_dwordx2 v[46:47], v149, s[64:65] offset:512
	global_load_dwordx2 v[48:49], v149, s[64:65] offset:1024
	global_load_dwordx2 v[50:51], v149, s[64:65] offset:1536
	global_load_dwordx4 v[52:55], v2, s[24:25]
	global_load_dwordx4 v[56:59], v2, s[24:25] offset:1024
	global_load_dwordx4 v[60:63], v2, s[24:25] offset:2048
	global_load_dwordx4 v[64:67], v2, s[24:25] offset:3072
	s_waitcnt vmcnt(0)
.Lrow_p4_top:
	v_lshlrev_b32_e32 v68, 16, v20
	v_and_b32_e32 v69, 0xffff0000, v20
	v_lshlrev_b32_e32 v70, 16, v21
	v_and_b32_e32 v71, 0xffff0000, v21
	v_lshlrev_b32_e32 v72, 16, v22
	v_and_b32_e32 v73, 0xffff0000, v22
	v_lshlrev_b32_e32 v74, 16, v23
	v_and_b32_e32 v75, 0xffff0000, v23
	v_lshlrev_b32_e32 v76, 16, v24
	v_and_b32_e32 v77, 0xffff0000, v24
	v_lshlrev_b32_e32 v78, 16, v25
	v_and_b32_e32 v79, 0xffff0000, v25
	v_lshlrev_b32_e32 v80, 16, v26
	v_and_b32_e32 v81, 0xffff0000, v26
	v_lshlrev_b32_e32 v82, 16, v27
	v_and_b32_e32 v83, 0xffff0000, v27
	v_mov_b64_e32 v[84:85], v[28:29]
	v_mov_b64_e32 v[86:87], v[30:31]
	v_mov_b64_e32 v[88:89], v[32:33]
	v_mov_b64_e32 v[90:91], v[34:35]
	v_mov_b64_e32 v[92:93], v[36:37]
	v_mov_b64_e32 v[94:95], v[38:39]
	v_mov_b64_e32 v[96:97], v[40:41]
	v_mov_b64_e32 v[98:99], v[42:43]
	v_mov_b32_e32 v150, v148
	v_lshlrev_b32_e32 v100, 16, v44
	v_and_b32_e32 v101, 0xffff0000, v44
	v_lshlrev_b32_e32 v102, 16, v45
	v_and_b32_e32 v103, 0xffff0000, v45
	v_lshlrev_b32_e32 v104, 16, v46
	v_and_b32_e32 v105, 0xffff0000, v46
	v_lshlrev_b32_e32 v106, 16, v47
	v_and_b32_e32 v107, 0xffff0000, v47
	v_lshlrev_b32_e32 v108, 16, v48
	v_and_b32_e32 v109, 0xffff0000, v48
	v_lshlrev_b32_e32 v110, 16, v49
	v_and_b32_e32 v111, 0xffff0000, v49
	v_lshlrev_b32_e32 v112, 16, v50
	v_and_b32_e32 v113, 0xffff0000, v50
	v_lshlrev_b32_e32 v114, 16, v51
	v_and_b32_e32 v115, 0xffff0000, v51
	v_mov_b64_e32 v[116:117], v[52:53]
	v_mov_b64_e32 v[118:119], v[54:55]
	v_mov_b64_e32 v[120:121], v[56:57]
	v_mov_b64_e32 v[122:123], v[58:59]
	v_mov_b64_e32 v[124:125], v[60:61]
	v_mov_b64_e32 v[126:127], v[62:63]
	v_mov_b64_e32 v[128:129], v[64:65]
	v_mov_b64_e32 v[130:131], v[66:67]
	v_mov_b32_e32 v151, v149
	s_add_u32 s49, s7, s32
	s_cmp_lt_u32 s49, 0x4400
	s_cbranch_scc0 .Lrow_p4_noload
	s_add_u32 s61, s49, s26
	s_cmp_lt_u32 s61, 0x4400
	s_cselect_b32 s61, s61, s49
	s_lshl_b32 s81, s49, 11
	v_add_u32_e32 v148, s81, v1
	s_cmp_lt_u32 s49, 0x4000
	s_cselect_b32 s10, s36, s38
	s_cselect_b32 s11, s37, s39
	s_cselect_b32 s81, 0, 0x4000
	s_sub_u32 s81, s49, s81
	s_lshl_b32 s81, s81, 12
	s_add_u32 s10, s10, s81
	s_addc_u32 s11, s11, 0
	s_lshl_b32 s81, s61, 11
	v_add_u32_e32 v149, s81, v1
	s_cmp_lt_u32 s61, 0x4000
	s_cselect_b32 s24, s36, s38
	s_cselect_b32 s25, s37, s39
	s_cselect_b32 s81, 0, 0x4000
	s_sub_u32 s81, s61, s81
	s_lshl_b32 s81, s81, 12
	s_add_u32 s24, s24, s81
	s_addc_u32 s25, s25, 0
	global_load_dwordx2 v[20:21], v148, s[64:65]
	global_load_dwordx2 v[22:23], v148, s[64:65] offset:512
	global_load_dwordx2 v[24:25], v148, s[64:65] offset:1024
	global_load_dwordx2 v[26:27], v148, s[64:65] offset:1536
	global_load_dwordx4 v[28:31], v2, s[10:11]
	global_load_dwordx4 v[32:35], v2, s[10:11] offset:1024
	global_load_dwordx4 v[36:39], v2, s[10:11] offset:2048
	global_load_dwordx4 v[40:43], v2, s[10:11] offset:3072
	global_load_dwordx2 v[44:45], v149, s[64:65]
	global_load_dwordx2 v[46:47], v149, s[64:65] offset:512
	global_load_dwordx2 v[48:49], v149, s[64:65] offset:1024
	global_load_dwordx2 v[50:51], v149, s[64:65] offset:1536
	global_load_dwordx4 v[52:55], v2, s[24:25]
	global_load_dwordx4 v[56:59], v2, s[24:25] offset:1024
	global_load_dwordx4 v[60:63], v2, s[24:25] offset:2048
	global_load_dwordx4 v[64:67], v2, s[24:25] offset:3072
.Lrow_p4_noload:
	v_mul_f32_e32 v152, v68, v68
	v_mul_f32_e32 v154, v69, v69
	v_fmac_f32_e32 v152, v70, v70
	v_fmac_f32_e32 v154, v71, v71
	v_fmac_f32_e32 v152, v72, v72
	v_fmac_f32_e32 v154, v73, v73
	v_fmac_f32_e32 v152, v74, v74
	v_fmac_f32_e32 v154, v75, v75
	v_fmac_f32_e32 v152, v76, v76
	v_fmac_f32_e32 v154, v77, v77
	v_fmac_f32_e32 v152, v78, v78
	v_fmac_f32_e32 v154, v79, v79
	v_fmac_f32_e32 v152, v80, v80
	v_fmac_f32_e32 v154, v81, v81
	v_fmac_f32_e32 v152, v82, v82
	v_fmac_f32_e32 v154, v83, v83
	v_add_f32_e32 v152, v152, v154
	v_mul_f32_e32 v153, v100, v100
	v_mul_f32_e32 v155, v101, v101
	v_fmac_f32_e32 v153, v102, v102
	v_fmac_f32_e32 v155, v103, v103
	v_fmac_f32_e32 v153, v104, v104
	v_fmac_f32_e32 v155, v105, v105
	v_fmac_f32_e32 v153, v106, v106
	v_fmac_f32_e32 v155, v107, v107
	v_fmac_f32_e32 v153, v108, v108
	v_fmac_f32_e32 v155, v109, v109
	v_fmac_f32_e32 v153, v110, v110
	v_fmac_f32_e32 v155, v111, v111
	v_fmac_f32_e32 v153, v112, v112
	v_fmac_f32_e32 v155, v113, v113
	v_fmac_f32_e32 v153, v114, v114
	v_fmac_f32_e32 v155, v115, v115
	v_add_f32_e32 v153, v153, v155
	s_nop 1
	v_add_f32_dpp v152, v152, v152 quad_perm:[1,0,3,2] row_mask:0xf bank_mask:0xf
	v_add_f32_dpp v153, v153, v153 quad_perm:[1,0,3,2] row_mask:0xf bank_mask:0xf
	s_nop 1
	v_add_f32_dpp v152, v152, v152 quad_perm:[2,3,0,1] row_mask:0xf bank_mask:0xf
	v_add_f32_dpp v153, v153, v153 quad_perm:[2,3,0,1] row_mask:0xf bank_mask:0xf
	s_nop 1
	v_add_f32_dpp v152, v152, v152 row_half_mirror row_mask:0xf bank_mask:0xf
	v_add_f32_dpp v153, v153, v153 row_half_mirror row_mask:0xf bank_mask:0xf
	s_nop 1
	v_add_f32_dpp v152, v152, v152 row_mirror row_mask:0xf bank_mask:0xf
	v_add_f32_dpp v153, v153, v153 row_mirror row_mask:0xf bank_mask:0xf
	s_nop 1
	v_readlane_b32 s82, v152, 0
	v_readlane_b32 s83, v152, 16
	v_readlane_b32 s84, v152, 32
	v_readlane_b32 s85, v152, 48
	s_nop 1
	v_mov_b32_e32 v156, s82
	v_add_f32_e32 v156, s83, v156
	v_add_f32_e32 v156, s84, v156
	v_add_f32_e32 v156, s85, v156
	v_readlane_b32 s82, v153, 0
	v_readlane_b32 s83, v153, 16
	v_readlane_b32 s84, v153, 32
	v_readlane_b32 s85, v153, 48
	s_nop 1
	v_mov_b32_e32 v158, s82
	v_add_f32_e32 v158, s83, v158
	v_add_f32_e32 v158, s84, v158
	v_add_f32_e32 v158, s85, v158
	v_fmamk_f32 v156, v156, 0x3a800000, v3
	v_fmamk_f32 v158, v158, 0x3a800000, v3
	v_rsq_f32_e32 v156, v156
	v_rsq_f32_e32 v158, v158
	s_nop 1
	v_pk_mul_f32 v[68:69], v[68:69], v[156:157] op_sel_hi:[1,0]
	v_pk_mul_f32 v[70:71], v[70:71], v[156:157] op_sel_hi:[1,0]
	v_pk_mul_f32 v[72:73], v[72:73], v[156:157] op_sel_hi:[1,0]
	v_pk_mul_f32 v[74:75], v[74:75], v[156:157] op_sel_hi:[1,0]
	v_pk_mul_f32 v[76:77], v[76:77], v[156:157] op_sel_hi:[1,0]
	v_pk_mul_f32 v[78:79], v[78:79], v[156:157] op_sel_hi:[1,0]
	v_pk_mul_f32 v[80:81], v[80:81], v[156:157] op_sel_hi:[1,0]
	v_pk_mul_f32 v[82:83], v[82:83], v[156:157] op_sel_hi:[1,0]
	v_pk_fma_f32 v[68:69], v[4:5], v[68:69], v[84:85]
	v_pk_fma_f32 v[70:71], v[6:7], v[70:71], v[86:87]
	v_pk_fma_f32 v[72:73], v[8:9], v[72:73], v[88:89]
	v_pk_fma_f32 v[74:75], v[10:11], v[74:75], v[90:91]
	v_pk_fma_f32 v[76:77], v[12:13], v[76:77], v[92:93]
	v_pk_fma_f32 v[78:79], v[14:15], v[78:79], v[94:95]
	v_pk_fma_f32 v[80:81], v[16:17], v[80:81], v[96:97]
	v_pk_fma_f32 v[82:83], v[18:19], v[82:83], v[98:99]
	v_cvt_pk_bf16_f32 v132, v68, v69
	v_cvt_pk_bf16_f32 v133, v70, v71
	v_cvt_pk_bf16_f32 v134, v72, v73
	v_cvt_pk_bf16_f32 v135, v74, v75
	v_cvt_pk_bf16_f32 v136, v76, v77
	v_cvt_pk_bf16_f32 v137, v78, v79
	v_cvt_pk_bf16_f32 v138, v80, v81
	v_cvt_pk_bf16_f32 v139, v82, v83
	global_store_dwordx2 v150, v[132:133], s[70:71]
	global_store_dwordx2 v150, v[134:135], s[70:71] offset:512
	global_store_dwordx2 v150, v[136:137], s[70:71] offset:1024
	global_store_dwordx2 v150, v[138:139], s[70:71] offset:1536
	v_pk_mul_f32 v[100:101], v[100:101], v[158:159] op_sel_hi:[1,0]
	v_pk_mul_f32 v[102:103], v[102:103], v[158:159] op_sel_hi:[1,0]
	v_pk_mul_f32 v[104:105], v[104:105], v[158:159] op_sel_hi:[1,0]
	v_pk_mul_f32 v[106:107], v[106:107], v[158:159] op_sel_hi:[1,0]
	v_pk_mul_f32 v[108:109], v[108:109], v[158:159] op_sel_hi:[1,0]
	v_pk_mul_f32 v[110:111], v[110:111], v[158:159] op_sel_hi:[1,0]
	v_pk_mul_f32 v[112:113], v[112:113], v[158:159] op_sel_hi:[1,0]
	v_pk_mul_f32 v[114:115], v[114:115], v[158:159] op_sel_hi:[1,0]
	v_pk_fma_f32 v[100:101], v[4:5], v[100:101], v[116:117]
	v_pk_fma_f32 v[102:103], v[6:7], v[102:103], v[118:119]
	v_pk_fma_f32 v[104:105], v[8:9], v[104:105], v[120:121]
	v_pk_fma_f32 v[106:107], v[10:11], v[106:107], v[122:123]
	v_pk_fma_f32 v[108:109], v[12:13], v[108:109], v[124:125]
	v_pk_fma_f32 v[110:111], v[14:15], v[110:111], v[126:127]
	v_pk_fma_f32 v[112:113], v[16:17], v[112:113], v[128:129]
	v_pk_fma_f32 v[114:115], v[18:19], v[114:115], v[130:131]
	v_cvt_pk_bf16_f32 v140, v100, v101
	v_cvt_pk_bf16_f32 v141, v102, v103
	v_cvt_pk_bf16_f32 v142, v104, v105
	v_cvt_pk_bf16_f32 v143, v106, v107
	v_cvt_pk_bf16_f32 v144, v108, v109
	v_cvt_pk_bf16_f32 v145, v110, v111
	v_cvt_pk_bf16_f32 v146, v112, v113
	v_cvt_pk_bf16_f32 v147, v114, v115
	global_store_dwordx2 v151, v[140:141], s[70:71]
	global_store_dwordx2 v151, v[142:143], s[70:71] offset:512
	global_store_dwordx2 v151, v[144:145], s[70:71] offset:1024
	global_store_dwordx2 v151, v[146:147], s[70:71] offset:1536
	s_cmp_lt_u32 s49, 0x4400
	s_cbranch_scc0 .Lrow_p4_done
	s_mov_b32 s7, s49
	s_waitcnt vmcnt(8)
	s_branch .Lrow_p4_top
.Lrow_p4_done:
.LBB0_814:
	s_or_b64 exec, exec, s[0:1]
	s_waitcnt vmcnt(0)
	v_readlane_b32 s68, v254, 30
	v_readlane_b32 s69, v254, 31
	s_barrier
	s_mov_b64 s[0:1], exec
	v_readlane_b32 s6, v254, 3
	v_readlane_b32 s7, v254, 4
	s_and_b64 s[6:7], s[0:1], s[6:7]
	s_xor_b64 s[0:1], s[6:7], s[0:1]
	s_mov_b64 exec, s[6:7]
	s_cbranch_execz .LBB0_867
	s_add_i32 s6, 0, 0x22ff0
	v_mov_b32_e32 v0, s6
	s_waitcnt vmcnt(0) expcnt(0) lgkmcnt(0)
	ds_read_b32 v2, v0
	s_add_i32 s6, 0, 0x22ff4
	v_mov_b32_e32 v0, s6
	ds_read_b32 v0, v0
	s_waitcnt lgkmcnt(1)
	v_cmp_ne_u32_e32 vcc, 0, v2
	s_cbranch_vccnz .LBB0_830
	v_readlane_b32 s6, v254, 0
	s_mul_i32 s24, s97, s6
	s_add_u32 s6, s94, 0x32c02a00
	s_addc_u32 s7, s95, 0
	s_add_u32 s8, s94, 0x32c02c00
	s_addc_u32 s9, s95, 0
	s_add_u32 s10, s94, 0x32c02d00
	s_addc_u32 s11, s95, 0
	s_add_u32 s14, s94, 0x32c02e00
	s_addc_u32 s15, s95, 0
	s_add_u32 s16, s94, 0x32c02f00
	s_addc_u32 s17, s95, 0
	s_add_u32 s18, s94, 0x32c03000
	s_addc_u32 s19, s95, 0
	s_add_u32 s20, s94, 0x32c03100
	s_addc_u32 s21, s95, 0
	s_add_u32 s22, s94, 0x32c03200
	s_addc_u32 s23, s95, 0
	s_add_u32 s36, s94, 0x32c03300
	s_addc_u32 s37, s95, 0
	s_add_u32 s38, s94, 0x32c03400
	s_addc_u32 s39, s95, 0
	s_add_u32 s40, s94, 0x32c03500
	s_addc_u32 s41, s95, 0
	s_add_u32 s42, s94, 0x32c03600
	s_addc_u32 s43, s95, 0
	s_add_u32 s56, s94, 0x32c03700
	s_addc_u32 s57, s95, 0
	s_add_u32 s58, s94, 0x32c03800
	s_addc_u32 s59, s95, 0
	s_add_u32 s60, s94, 0x32c03900
	s_addc_u32 s61, s95, 0
	s_add_u32 s62, s94, 0x32c03a00
	s_addc_u32 s63, s95, 0
	s_add_u32 s64, s94, 0x32c03b00
	s_mul_i32 s24, s24, s96
	s_addc_u32 s65, s95, 0
	s_mov_b32 s25, 1
	v_mov_b32_e32 v16, 0
	s_branch .LBB0_818

.LBB0_940:
	s_or_b64 exec, exec, s[0:1]
	v_mov_b32_e32 v12, v198
	s_waitcnt lgkmcnt(0)
	s_barrier
	v_readlane_b32 s0, v254, 29
	v_ashrrev_i32_e32 v0, 6, v12
	s_nop 0
	v_add_u32_e32 v8, s0, v0
	s_movk_i32 s0, 0x4400
	v_cmp_gt_i32_e32 vcc, s0, v8
	s_and_saveexec_b64 s[0:1], vcc
	s_cbranch_execz .LBB0_943
	s_ashr_i32 s73, s72, 31
	v_and_b32_e32 v0, 63, v198
	v_lshlrev_b32_e32 v1, 4, v0
	v_lshlrev_b32_e32 v2, 5, v0
	v_mov_b32_e32 v3, 0x358637bd
	s_add_u32 s76, s50, 0x1000
	s_addc_u32 s77, s51, 0
	global_load_dwordx4 v[4:7], v2, s[76:77]
	global_load_dwordx4 v[8:11], v2, s[76:77] offset:16
	global_load_dwordx4 v[12:15], v2, s[76:77] offset:2048
	global_load_dwordx4 v[16:19], v2, s[76:77] offset:2064
	s_add_u32 s64, s94, 0x12002800
	s_addc_u32 s65, s95, 0
	s_add_u32 s70, s94, 0x2102800
	s_addc_u32 s71, s95, 0
	v_lshrrev_b32_e32 v122, 6, v198
	s_lshl_b32 s26, s96, 3
	v_readfirstlane_b32 s7, v122
	s_mul_i32 s32, s26, 3
	s_nop 3
	s_lshl_b32 s81, s2, 3
	s_add_u32 s7, s7, s81
	s_add_u32 s61, s7, s26
	s_add_u32 s63, s61, s26
	s_cmp_lt_u32 s61, 0x4400
	s_cselect_b32 s61, s61, s7
	s_cmp_lt_u32 s63, 0x4400
	s_cselect_b32 s63, s63, s7
	s_lshl_b32 s81, s7, 11
	v_add_u32_e32 v116, s81, v1
	s_lshl_b32 s81, s61, 11
	v_add_u32_e32 v117, s81, v1
	s_lshl_b32 s81, s63, 11
	v_add_u32_e32 v118, s81, v1
	global_load_dwordx4 v[20:23], v116, s[64:65]
	global_load_dwordx4 v[24:27], v116, s[64:65] offset:1024
	global_load_dwordx4 v[28:31], v117, s[64:65]
	global_load_dwordx4 v[32:35], v117, s[64:65] offset:1024
	global_load_dwordx4 v[36:39], v118, s[64:65]
	global_load_dwordx4 v[40:43], v118, s[64:65] offset:1024
	s_waitcnt vmcnt(0)
.Lrow_p6_top:
	v_lshlrev_b32_e32 v44, 16, v20
	v_and_b32_e32 v45, 0xffff0000, v20
	v_lshlrev_b32_e32 v46, 16, v21
	v_and_b32_e32 v47, 0xffff0000, v21
	v_lshlrev_b32_e32 v48, 16, v22
	v_and_b32_e32 v49, 0xffff0000, v22
	v_lshlrev_b32_e32 v50, 16, v23
	v_and_b32_e32 v51, 0xffff0000, v23
	v_lshlrev_b32_e32 v52, 16, v24
	v_and_b32_e32 v53, 0xffff0000, v24
	v_lshlrev_b32_e32 v54, 16, v25
	v_and_b32_e32 v55, 0xffff0000, v25
	v_lshlrev_b32_e32 v56, 16, v26
	v_and_b32_e32 v57, 0xffff0000, v26
	v_lshlrev_b32_e32 v58, 16, v27
	v_and_b32_e32 v59, 0xffff0000, v27
	v_mov_b32_e32 v119, v116
	v_lshlrev_b32_e32 v60, 16, v28
	v_and_b32_e32 v61, 0xffff0000, v28
	v_lshlrev_b32_e32 v62, 16, v29
	v_and_b32_e32 v63, 0xffff0000, v29
	v_lshlrev_b32_e32 v64, 16, v30
	v_and_b32_e32 v65, 0xffff0000, v30
	v_lshlrev_b32_e32 v66, 16, v31
	v_and_b32_e32 v67, 0xffff0000, v31
	v_lshlrev_b32_e32 v68, 16, v32
	v_and_b32_e32 v69, 0xffff0000, v32
	v_lshlrev_b32_e32 v70, 16, v33
	v_and_b32_e32 v71, 0xffff0000, v33
	v_lshlrev_b32_e32 v72, 16, v34
	v_and_b32_e32 v73, 0xffff0000, v34
	v_lshlrev_b32_e32 v74, 16, v35
	v_and_b32_e32 v75, 0xffff0000, v35
	v_mov_b32_e32 v120, v117
	v_lshlrev_b32_e32 v76, 16, v36
	v_and_b32_e32 v77, 0xffff0000, v36
	v_lshlrev_b32_e32 v78, 16, v37
	v_and_b32_e32 v79, 0xffff0000, v37
	v_lshlrev_b32_e32 v80, 16, v38
	v_and_b32_e32 v81, 0xffff0000, v38
	v_lshlrev_b32_e32 v82, 16, v39
	v_and_b32_e32 v83, 0xffff0000, v39
	v_lshlrev_b32_e32 v84, 16, v40
	v_and_b32_e32 v85, 0xffff0000, v40
	v_lshlrev_b32_e32 v86, 16, v41
	v_and_b32_e32 v87, 0xffff0000, v41
	v_lshlrev_b32_e32 v88, 16, v42
	v_and_b32_e32 v89, 0xffff0000, v42
	v_lshlrev_b32_e32 v90, 16, v43
	v_and_b32_e32 v91, 0xffff0000, v43
	v_mov_b32_e32 v121, v118
	s_add_u32 s49, s7, s32
	s_cmp_lt_u32 s49, 0x4400
	s_cbranch_scc0 .Lrow_p6_noload
	s_add_u32 s61, s49, s26
	s_add_u32 s63, s61, s26
	s_cmp_lt_u32 s61, 0x4400
	s_cselect_b32 s61, s61, s49
	s_cmp_lt_u32 s63, 0x4400
	s_cselect_b32 s63, s63, s49
	s_lshl_b32 s81, s49, 11
	v_add_u32_e32 v116, s81, v1
	s_lshl_b32 s81, s61, 11
	v_add_u32_e32 v117, s81, v1
	s_lshl_b32 s81, s63, 11
	v_add_u32_e32 v118, s81, v1
	global_load_dwordx4 v[20:23], v116, s[64:65]
	global_load_dwordx4 v[24:27], v116, s[64:65] offset:1024
	global_load_dwordx4 v[28:31], v117, s[64:65]
	global_load_dwordx4 v[32:35], v117, s[64:65] offset:1024
	global_load_dwordx4 v[36:39], v118, s[64:65]
	global_load_dwordx4 v[40:43], v118, s[64:65] offset:1024
.Lrow_p6_noload:
	v_mul_f32_e32 v122, v44, v44
	v_mul_f32_e32 v125, v45, v45
	v_fmac_f32_e32 v122, v46, v46
	v_fmac_f32_e32 v125, v47, v47
	v_fmac_f32_e32 v122, v48, v48
	v_fmac_f32_e32 v125, v49, v49
	v_fmac_f32_e32 v122, v50, v50
	v_fmac_f32_e32 v125, v51, v51
	v_fmac_f32_e32 v122, v52, v52
	v_fmac_f32_e32 v125, v53, v53
	v_fmac_f32_e32 v122, v54, v54
	v_fmac_f32_e32 v125, v55, v55
	v_fmac_f32_e32 v122, v56, v56
	v_fmac_f32_e32 v125, v57, v57
	v_fmac_f32_e32 v122, v58, v58
	v_fmac_f32_e32 v125, v59, v59
	v_add_f32_e32 v122, v122, v125
	v_mul_f32_e32 v123, v60, v60
	v_mul_f32_e32 v126, v61, v61
	v_fmac_f32_e32 v123, v62, v62
	v_fmac_f32_e32 v126, v63, v63
	v_fmac_f32_e32 v123, v64, v64
	v_fmac_f32_e32 v126, v65, v65
	v_fmac_f32_e32 v123, v66, v66
	v_fmac_f32_e32 v126, v67, v67
	v_fmac_f32_e32 v123, v68, v68
	v_fmac_f32_e32 v126, v69, v69
	v_fmac_f32_e32 v123, v70, v70
	v_fmac_f32_e32 v126, v71, v71
	v_fmac_f32_e32 v123, v72, v72
	v_fmac_f32_e32 v126, v73, v73
	v_fmac_f32_e32 v123, v74, v74
	v_fmac_f32_e32 v126, v75, v75
	v_add_f32_e32 v123, v123, v126
	v_mul_f32_e32 v124, v76, v76
	v_mul_f32_e32 v127, v77, v77
	v_fmac_f32_e32 v124, v78, v78
	v_fmac_f32_e32 v127, v79, v79
	v_fmac_f32_e32 v124, v80, v80
	v_fmac_f32_e32 v127, v81, v81
	v_fmac_f32_e32 v124, v82, v82
	v_fmac_f32_e32 v127, v83, v83
	v_fmac_f32_e32 v124, v84, v84
	v_fmac_f32_e32 v127, v85, v85
	v_fmac_f32_e32 v124, v86, v86
	v_fmac_f32_e32 v127, v87, v87
	v_fmac_f32_e32 v124, v88, v88
	v_fmac_f32_e32 v127, v89, v89
	v_fmac_f32_e32 v124, v90, v90
	v_fmac_f32_e32 v127, v91, v91
	v_add_f32_e32 v124, v124, v127
	s_nop 1
	v_add_f32_dpp v122, v122, v122 quad_perm:[1,0,3,2] row_mask:0xf bank_mask:0xf
	v_add_f32_dpp v123, v123, v123 quad_perm:[1,0,3,2] row_mask:0xf bank_mask:0xf
	v_add_f32_dpp v124, v124, v124 quad_perm:[1,0,3,2] row_mask:0xf bank_mask:0xf
	s_nop 1
	v_add_f32_dpp v122, v122, v122 quad_perm:[2,3,0,1] row_mask:0xf bank_mask:0xf
	v_add_f32_dpp v123, v123, v123 quad_perm:[2,3,0,1] row_mask:0xf bank_mask:0xf
	v_add_f32_dpp v124, v124, v124 quad_perm:[2,3,0,1] row_mask:0xf bank_mask:0xf
	s_nop 1
	v_add_f32_dpp v122, v122, v122 row_half_mirror row_mask:0xf bank_mask:0xf
	v_add_f32_dpp v123, v123, v123 row_half_mirror row_mask:0xf bank_mask:0xf
	v_add_f32_dpp v124, v124, v124 row_half_mirror row_mask:0xf bank_mask:0xf
	s_nop 1
	v_add_f32_dpp v122, v122, v122 row_mirror row_mask:0xf bank_mask:0xf
	v_add_f32_dpp v123, v123, v123 row_mirror row_mask:0xf bank_mask:0xf
	v_add_f32_dpp v124, v124, v124 row_mirror row_mask:0xf bank_mask:0xf
	s_nop 1
	v_readlane_b32 s82, v122, 0
	v_readlane_b32 s83, v122, 16
	v_readlane_b32 s84, v122, 32
	v_readlane_b32 s85, v122, 48
	s_nop 1
	v_mov_b32_e32 v128, s82
	v_add_f32_e32 v128, s83, v128
	v_add_f32_e32 v128, s84, v128
	v_add_f32_e32 v128, s85, v128
	v_readlane_b32 s82, v123, 0
	v_readlane_b32 s83, v123, 16
	v_readlane_b32 s84, v123, 32
	v_readlane_b32 s85, v123, 48
	s_nop 1
	v_mov_b32_e32 v130, s82
	v_add_f32_e32 v130, s83, v130
	v_add_f32_e32 v130, s84, v130
	v_add_f32_e32 v130, s85, v130
	v_readlane_b32 s82, v124, 0
	v_readlane_b32 s83, v124, 16
	v_readlane_b32 s84, v124, 32
	v_readlane_b32 s85, v124, 48
	s_nop 1
	v_mov_b32_e32 v132, s82
	v_add_f32_e32 v132, s83, v132
	v_add_f32_e32 v132, s84, v132
	v_add_f32_e32 v132, s85, v132
	v_fmamk_f32 v128, v128, 0x3a800000, v3
	v_fmamk_f32 v130, v130, 0x3a800000, v3
	v_fmamk_f32 v132, v132, 0x3a800000, v3
	v_rsq_f32_e32 v128, v128
	v_rsq_f32_e32 v130, v130
	v_rsq_f32_e32 v132, v132
	s_nop 1
	v_pk_mul_f32 v[44:45], v[44:45], v[128:129] op_sel_hi:[1,0]
	v_pk_mul_f32 v[46:47], v[46:47], v[128:129] op_sel_hi:[1,0]
	v_pk_mul_f32 v[48:49], v[48:49], v[128:129] op_sel_hi:[1,0]
	v_pk_mul_f32 v[50:51], v[50:51], v[128:129] op_sel_hi:[1,0]
	v_pk_mul_f32 v[52:53], v[52:53], v[128:129] op_sel_hi:[1,0]
	v_pk_mul_f32 v[54:55], v[54:55], v[128:129] op_sel_hi:[1,0]
	v_pk_mul_f32 v[56:57], v[56:57], v[128:129] op_sel_hi:[1,0]
	v_pk_mul_f32 v[58:59], v[58:59], v[128:129] op_sel_hi:[1,0]
	v_pk_mul_f32 v[44:45], v[44:45], v[4:5]
	v_pk_mul_f32 v[46:47], v[46:47], v[6:7]
	v_pk_mul_f32 v[48:49], v[48:49], v[8:9]
	v_pk_mul_f32 v[50:51], v[50:51], v[10:11]
	v_pk_mul_f32 v[52:53], v[52:53], v[12:13]
	v_pk_mul_f32 v[54:55], v[54:55], v[14:15]
	v_pk_mul_f32 v[56:57], v[56:57], v[16:17]
	v_pk_mul_f32 v[58:59], v[58:59], v[18:19]
	v_cvt_pk_bf16_f32 v92, v44, v45
	v_cvt_pk_bf16_f32 v93, v46, v47
	v_cvt_pk_bf16_f32 v94, v48, v49
	v_cvt_pk_bf16_f32 v95, v50, v51
	v_cvt_pk_bf16_f32 v96, v52, v53
	v_cvt_pk_bf16_f32 v97, v54, v55
	v_cvt_pk_bf16_f32 v98, v56, v57
	v_cvt_pk_bf16_f32 v99, v58, v59
	global_store_dwordx4 v119, v[92:95], s[70:71]
	global_store_dwordx4 v119, v[96:99], s[70:71] offset:1024
	v_pk_mul_f32 v[60:61], v[60:61], v[130:131] op_sel_hi:[1,0]
	v_pk_mul_f32 v[62:63], v[62:63], v[130:131] op_sel_hi:[1,0]
	v_pk_mul_f32 v[64:65], v[64:65], v[130:131] op_sel_hi:[1,0]
	v_pk_mul_f32 v[66:67], v[66:67], v[130:131] op_sel_hi:[1,0]
	v_pk_mul_f32 v[68:69], v[68:69], v[130:131] op_sel_hi:[1,0]
	v_pk_mul_f32 v[70:71], v[70:71], v[130:131] op_sel_hi:[1,0]
	v_pk_mul_f32 v[72:73], v[72:73], v[130:131] op_sel_hi:[1,0]
	v_pk_mul_f32 v[74:75], v[74:75], v[130:131] op_sel_hi:[1,0]
	v_pk_mul_f32 v[60:61], v[60:61], v[4:5]
	v_pk_mul_f32 v[62:63], v[62:63], v[6:7]
	v_pk_mul_f32 v[64:65], v[64:65], v[8:9]
	v_pk_mul_f32 v[66:67], v[66:67], v[10:11]
	v_pk_mul_f32 v[68:69], v[68:69], v[12:13]
	v_pk_mul_f32 v[70:71], v[70:71], v[14:15]
	v_pk_mul_f32 v[72:73], v[72:73], v[16:17]
	v_pk_mul_f32 v[74:75], v[74:75], v[18:19]
	v_cvt_pk_bf16_f32 v100, v60, v61
	v_cvt_pk_bf16_f32 v101, v62, v63
	v_cvt_pk_bf16_f32 v102, v64, v65
	v_cvt_pk_bf16_f32 v103, v66, v67
	v_cvt_pk_bf16_f32 v104, v68, v69
	v_cvt_pk_bf16_f32 v105, v70, v71
	v_cvt_pk_bf16_f32 v106, v72, v73
	v_cvt_pk_bf16_f32 v107, v74, v75
	global_store_dwordx4 v120, v[100:103], s[70:71]
	global_store_dwordx4 v120, v[104:107], s[70:71] offset:1024
	v_pk_mul_f32 v[76:77], v[76:77], v[132:133] op_sel_hi:[1,0]
	v_pk_mul_f32 v[78:79], v[78:79], v[132:133] op_sel_hi:[1,0]
	v_pk_mul_f32 v[80:81], v[80:81], v[132:133] op_sel_hi:[1,0]
	v_pk_mul_f32 v[82:83], v[82:83], v[132:133] op_sel_hi:[1,0]
	v_pk_mul_f32 v[84:85], v[84:85], v[132:133] op_sel_hi:[1,0]
	v_pk_mul_f32 v[86:87], v[86:87], v[132:133] op_sel_hi:[1,0]
	v_pk_mul_f32 v[88:89], v[88:89], v[132:133] op_sel_hi:[1,0]
	v_pk_mul_f32 v[90:91], v[90:91], v[132:133] op_sel_hi:[1,0]
	v_pk_mul_f32 v[76:77], v[76:77], v[4:5]
	v_pk_mul_f32 v[78:79], v[78:79], v[6:7]
	v_pk_mul_f32 v[80:81], v[80:81], v[8:9]
	v_pk_mul_f32 v[82:83], v[82:83], v[10:11]
	v_pk_mul_f32 v[84:85], v[84:85], v[12:13]
	v_pk_mul_f32 v[86:87], v[86:87], v[14:15]
	v_pk_mul_f32 v[88:89], v[88:89], v[16:17]
	v_pk_mul_f32 v[90:91], v[90:91], v[18:19]
	v_cvt_pk_bf16_f32 v108, v76, v77
	v_cvt_pk_bf16_f32 v109, v78, v79
	v_cvt_pk_bf16_f32 v110, v80, v81
	v_cvt_pk_bf16_f32 v111, v82, v83
	v_cvt_pk_bf16_f32 v112, v84, v85
	v_cvt_pk_bf16_f32 v113, v86, v87
	v_cvt_pk_bf16_f32 v114, v88, v89
	v_cvt_pk_bf16_f32 v115, v90, v91
	global_store_dwordx4 v121, v[108:111], s[70:71]
	global_store_dwordx4 v121, v[112:115], s[70:71] offset:1024
	s_cmp_lt_u32 s49, 0x4400
	s_cbranch_scc0 .Lrow_p6_done
	s_mov_b32 s7, s49
	s_waitcnt vmcnt(6)
	s_branch .Lrow_p6_top
.Lrow_p6_done:
.LBB0_943:
	v_writelane_b32 v254, s72, 27
	s_nop 1
	v_writelane_b32 v254, s73, 28
	s_or_b64 exec, exec, s[0:1]
	s_waitcnt vmcnt(0)
	s_barrier
	s_mov_b64 s[0:1], exec
	v_readlane_b32 s6, v254, 3
	v_readlane_b32 s7, v254, 4
	s_and_b64 s[6:7], s[0:1], s[6:7]
	s_xor_b64 s[0:1], s[6:7], s[0:1]
	s_mov_b64 exec, s[6:7]
	s_cbranch_execz .LBB0_996
	s_add_i32 s6, 0, 0x22ff0
	v_mov_b32_e32 v0, s6
	s_waitcnt vmcnt(0) expcnt(0) lgkmcnt(0)
	ds_read_b32 v2, v0
	s_add_i32 s6, 0, 0x22ff4
	v_mov_b32_e32 v0, s6
	ds_read_b32 v0, v0
	s_waitcnt lgkmcnt(1)
	v_cmp_ne_u32_e32 vcc, 0, v2
	s_cbranch_vccnz .LBB0_959
	v_readlane_b32 s6, v254, 0
	s_mul_i32 s24, s97, s6
	s_add_u32 s6, s94, 0x32c02a00
	s_addc_u32 s7, s95, 0
	s_add_u32 s8, s94, 0x32c02c00
	s_addc_u32 s9, s95, 0
	s_add_u32 s10, s94, 0x32c02d00
	s_addc_u32 s11, s95, 0
	s_add_u32 s14, s94, 0x32c02e00
	s_addc_u32 s15, s95, 0
	s_add_u32 s16, s94, 0x32c02f00
	s_addc_u32 s17, s95, 0
	s_add_u32 s18, s94, 0x32c03000
	s_addc_u32 s19, s95, 0
	s_add_u32 s20, s94, 0x32c03100
	s_addc_u32 s21, s95, 0
	s_add_u32 s22, s94, 0x32c03200
	s_addc_u32 s23, s95, 0
	s_add_u32 s36, s94, 0x32c03300
	s_addc_u32 s37, s95, 0
	s_add_u32 s38, s94, 0x32c03400
	s_addc_u32 s39, s95, 0
	s_add_u32 s40, s94, 0x32c03500
	s_addc_u32 s41, s95, 0
	s_add_u32 s42, s94, 0x32c03600
	s_addc_u32 s43, s95, 0
	s_add_u32 s50, s94, 0x32c03700
	s_addc_u32 s51, s95, 0
	s_add_u32 s52, s94, 0x32c03800
	s_addc_u32 s53, s95, 0
	s_add_u32 s56, s94, 0x32c03900
	s_addc_u32 s57, s95, 0
	s_add_u32 s58, s94, 0x32c03a00
	s_addc_u32 s59, s95, 0
	s_add_u32 s60, s94, 0x32c03b00
	s_mul_i32 s24, s24, s96
	s_addc_u32 s61, s95, 0
	s_mov_b32 s25, 1
	v_mov_b32_e32 v16, 0
	s_branch .LBB0_947

.LBB0_1547:
	s_or_b64 exec, exec, s[0:1]
	v_mov_b32_e32 v12, v198
	s_waitcnt lgkmcnt(0)
	s_barrier
	v_readlane_b32 s0, v254, 29
	v_ashrrev_i32_e32 v0, 6, v12
	s_nop 0
	v_add_u32_e32 v4, s0, v0
	s_movk_i32 s0, 0x4400
	v_cmp_gt_i32_e32 vcc, s0, v4
	s_and_saveexec_b64 s[0:1], vcc
	v_readlane_b32 s24, v254, 27
	v_readlane_b32 s25, v254, 28
	s_cbranch_execz .LBB0_1550
	v_readlane_b32 s16, v254, 13
	v_readlane_b32 s18, v254, 15
	v_readlane_b32 s19, v254, 16
	v_readlane_b32 s20, v254, 17
	v_readlane_b32 s21, v254, 18
	v_readlane_b32 s22, v254, 19
	v_readlane_b32 s23, v254, 20
	v_and_b32_e32 v0, 63, v198
	v_lshlrev_b32_e32 v1, 4, v0
	v_lshlrev_b32_e32 v2, 5, v0
	v_mov_b32_e32 v3, 0x358637bd
	v_readlane_b32 s76, v254, 5
	v_readlane_b32 s77, v254, 6
	s_nop 1
	s_add_u32 s76, s76, 0x1000
	s_addc_u32 s77, s77, 0
	s_nop 4
	global_load_dwordx4 v[4:7], v2, s[76:77]
	global_load_dwordx4 v[8:11], v2, s[76:77] offset:16
	global_load_dwordx4 v[12:15], v2, s[76:77] offset:2048
	global_load_dwordx4 v[16:19], v2, s[76:77] offset:2064
	s_add_u32 s64, s94, 0x9802800
	s_addc_u32 s65, s95, 0
	s_add_u32 s66, s94, 0x12002800
	s_addc_u32 s67, s95, 0
	s_add_u32 s70, s94, 0x2102800
	s_addc_u32 s71, s95, 0
	v_lshrrev_b32_e32 v194, 6, v198
	s_lshl_b32 s26, s96, 3
	v_readfirstlane_b32 s7, v194
	s_mul_i32 s32, s26, 3
	s_nop 3
	s_lshl_b32 s81, s2, 3
	s_add_u32 s7, s7, s81
	s_add_u32 s61, s7, s26
	s_add_u32 s63, s61, s26
	s_cmp_lt_u32 s61, 0x4400
	s_cselect_b32 s61, s61, s7
	s_cmp_lt_u32 s63, 0x4400
	s_cselect_b32 s63, s63, s7
	s_lshl_b32 s81, s7, 11
	v_add_u32_e32 v188, s81, v1
	s_lshl_b32 s81, s61, 11
	v_add_u32_e32 v189, s81, v1
	s_lshl_b32 s81, s63, 11
	v_add_u32_e32 v190, s81, v1
	global_load_dwordx4 v[20:23], v188, s[64:65]
	global_load_dwordx4 v[24:27], v188, s[64:65] offset:1024
	global_load_dwordx4 v[28:31], v188, s[66:67]
	global_load_dwordx4 v[32:35], v188, s[66:67] offset:1024
	global_load_dwordx4 v[36:39], v189, s[64:65]
	global_load_dwordx4 v[40:43], v189, s[64:65] offset:1024
	global_load_dwordx4 v[44:47], v189, s[66:67]
	global_load_dwordx4 v[48:51], v189, s[66:67] offset:1024
	global_load_dwordx4 v[52:55], v190, s[64:65]
	global_load_dwordx4 v[56:59], v190, s[64:65] offset:1024
	global_load_dwordx4 v[60:63], v190, s[66:67]
	global_load_dwordx4 v[64:67], v190, s[66:67] offset:1024
	s_waitcnt vmcnt(0)
.Lrow_p12_top:
	v_lshlrev_b32_e32 v68, 16, v20
	v_and_b32_e32 v69, 0xffff0000, v20
	v_lshlrev_b32_e32 v70, 16, v21
	v_and_b32_e32 v71, 0xffff0000, v21
	v_lshlrev_b32_e32 v72, 16, v22
	v_and_b32_e32 v73, 0xffff0000, v22
	v_lshlrev_b32_e32 v74, 16, v23
	v_and_b32_e32 v75, 0xffff0000, v23
	v_lshlrev_b32_e32 v76, 16, v24
	v_and_b32_e32 v77, 0xffff0000, v24
	v_lshlrev_b32_e32 v78, 16, v25
	v_and_b32_e32 v79, 0xffff0000, v25
	v_lshlrev_b32_e32 v80, 16, v26
	v_and_b32_e32 v81, 0xffff0000, v26
	v_lshlrev_b32_e32 v82, 16, v27
	v_and_b32_e32 v83, 0xffff0000, v27
	v_lshlrev_b32_e32 v84, 16, v28
	v_and_b32_e32 v85, 0xffff0000, v28
	v_lshlrev_b32_e32 v86, 16, v29
	v_and_b32_e32 v87, 0xffff0000, v29
	v_lshlrev_b32_e32 v88, 16, v30
	v_and_b32_e32 v89, 0xffff0000, v30
	v_lshlrev_b32_e32 v90, 16, v31
	v_and_b32_e32 v91, 0xffff0000, v31
	v_lshlrev_b32_e32 v92, 16, v32
	v_and_b32_e32 v93, 0xffff0000, v32
	v_lshlrev_b32_e32 v94, 16, v33
	v_and_b32_e32 v95, 0xffff0000, v33
	v_lshlrev_b32_e32 v96, 16, v34
	v_and_b32_e32 v97, 0xffff0000, v34
	v_lshlrev_b32_e32 v98, 16, v35
	v_and_b32_e32 v99, 0xffff0000, v35
	v_mov_b32_e32 v191, v188
	v_lshlrev_b32_e32 v100, 16, v36
	v_and_b32_e32 v101, 0xffff0000, v36
	v_lshlrev_b32_e32 v102, 16, v37
	v_and_b32_e32 v103, 0xffff0000, v37
	v_lshlrev_b32_e32 v104, 16, v38
	v_and_b32_e32 v105, 0xffff0000, v38
	v_lshlrev_b32_e32 v106, 16, v39
	v_and_b32_e32 v107, 0xffff0000, v39
	v_lshlrev_b32_e32 v108, 16, v40
	v_and_b32_e32 v109, 0xffff0000, v40
	v_lshlrev_b32_e32 v110, 16, v41
	v_and_b32_e32 v111, 0xffff0000, v41
	v_lshlrev_b32_e32 v112, 16, v42
	v_and_b32_e32 v113, 0xffff0000, v42
	v_lshlrev_b32_e32 v114, 16, v43
	v_and_b32_e32 v115, 0xffff0000, v43
	v_lshlrev_b32_e32 v116, 16, v44
	v_and_b32_e32 v117, 0xffff0000, v44
	v_lshlrev_b32_e32 v118, 16, v45
	v_and_b32_e32 v119, 0xffff0000, v45
	v_lshlrev_b32_e32 v120, 16, v46
	v_and_b32_e32 v121, 0xffff0000, v46
	v_lshlrev_b32_e32 v122, 16, v47
	v_and_b32_e32 v123, 0xffff0000, v47
	v_lshlrev_b32_e32 v124, 16, v48
	v_and_b32_e32 v125, 0xffff0000, v48
	v_lshlrev_b32_e32 v126, 16, v49
	v_and_b32_e32 v127, 0xffff0000, v49
	v_lshlrev_b32_e32 v128, 16, v50
	v_and_b32_e32 v129, 0xffff0000, v50
	v_lshlrev_b32_e32 v130, 16, v51
	v_and_b32_e32 v131, 0xffff0000, v51
	v_mov_b32_e32 v192, v189
	v_lshlrev_b32_e32 v132, 16, v52
	v_and_b32_e32 v133, 0xffff0000, v52
	v_lshlrev_b32_e32 v134, 16, v53
	v_and_b32_e32 v135, 0xffff0000, v53
	v_lshlrev_b32_e32 v136, 16, v54
	v_and_b32_e32 v137, 0xffff0000, v54
	v_lshlrev_b32_e32 v138, 16, v55
	v_and_b32_e32 v139, 0xffff0000, v55
	v_lshlrev_b32_e32 v140, 16, v56
	v_and_b32_e32 v141, 0xffff0000, v56
	v_lshlrev_b32_e32 v142, 16, v57
	v_and_b32_e32 v143, 0xffff0000, v57
	v_lshlrev_b32_e32 v144, 16, v58
	v_and_b32_e32 v145, 0xffff0000, v58
	v_lshlrev_b32_e32 v146, 16, v59
	v_and_b32_e32 v147, 0xffff0000, v59
	v_lshlrev_b32_e32 v148, 16, v60
	v_and_b32_e32 v149, 0xffff0000, v60
	v_lshlrev_b32_e32 v150, 16, v61
	v_and_b32_e32 v151, 0xffff0000, v61
	v_lshlrev_b32_e32 v152, 16, v62
	v_and_b32_e32 v153, 0xffff0000, v62
	v_lshlrev_b32_e32 v154, 16, v63
	v_and_b32_e32 v155, 0xffff0000, v63
	v_lshlrev_b32_e32 v156, 16, v64
	v_and_b32_e32 v157, 0xffff0000, v64
	v_lshlrev_b32_e32 v158, 16, v65
	v_and_b32_e32 v159, 0xffff0000, v65
	v_lshlrev_b32_e32 v160, 16, v66
	v_and_b32_e32 v161, 0xffff0000, v66
	v_lshlrev_b32_e32 v162, 16, v67
	v_and_b32_e32 v163, 0xffff0000, v67
	v_mov_b32_e32 v193, v190
	s_add_u32 s49, s7, s32
	s_cmp_lt_u32 s49, 0x4400
	s_cbranch_scc0 .Lrow_p12_noload
	s_add_u32 s61, s49, s26
	s_add_u32 s63, s61, s26
	s_cmp_lt_u32 s61, 0x4400
	s_cselect_b32 s61, s61, s49
	s_cmp_lt_u32 s63, 0x4400
	s_cselect_b32 s63, s63, s49
	s_lshl_b32 s81, s49, 11
	v_add_u32_e32 v188, s81, v1
	s_lshl_b32 s81, s61, 11
	v_add_u32_e32 v189, s81, v1
	s_lshl_b32 s81, s63, 11
	v_add_u32_e32 v190, s81, v1
	global_load_dwordx4 v[20:23], v188, s[64:65]
	global_load_dwordx4 v[24:27], v188, s[64:65] offset:1024
	global_load_dwordx4 v[28:31], v188, s[66:67]
	global_load_dwordx4 v[32:35], v188, s[66:67] offset:1024
	global_load_dwordx4 v[36:39], v189, s[64:65]
	global_load_dwordx4 v[40:43], v189, s[64:65] offset:1024
	global_load_dwordx4 v[44:47], v189, s[66:67]
	global_load_dwordx4 v[48:51], v189, s[66:67] offset:1024
	global_load_dwordx4 v[52:55], v190, s[64:65]
	global_load_dwordx4 v[56:59], v190, s[64:65] offset:1024
	global_load_dwordx4 v[60:63], v190, s[66:67]
	global_load_dwordx4 v[64:67], v190, s[66:67] offset:1024
.Lrow_p12_noload:
	v_mul_f32_e32 v194, v68, v68
	v_mul_f32_e32 v197, v69, v69
	v_fmac_f32_e32 v194, v70, v70
	v_fmac_f32_e32 v197, v71, v71
	v_fmac_f32_e32 v194, v72, v72
	v_fmac_f32_e32 v197, v73, v73
	v_fmac_f32_e32 v194, v74, v74
	v_fmac_f32_e32 v197, v75, v75
	v_fmac_f32_e32 v194, v76, v76
	v_fmac_f32_e32 v197, v77, v77
	v_fmac_f32_e32 v194, v78, v78
	v_fmac_f32_e32 v197, v79, v79
	v_fmac_f32_e32 v194, v80, v80
	v_fmac_f32_e32 v197, v81, v81
	v_fmac_f32_e32 v194, v82, v82
	v_fmac_f32_e32 v197, v83, v83
	v_add_f32_e32 v194, v194, v197
	v_mul_f32_e32 v195, v100, v100
	v_mul_f32_e32 v200, v101, v101
	v_fmac_f32_e32 v195, v102, v102
	v_fmac_f32_e32 v200, v103, v103
	v_fmac_f32_e32 v195, v104, v104
	v_fmac_f32_e32 v200, v105, v105
	v_fmac_f32_e32 v195, v106, v106
	v_fmac_f32_e32 v200, v107, v107
	v_fmac_f32_e32 v195, v108, v108
	v_fmac_f32_e32 v200, v109, v109
	v_fmac_f32_e32 v195, v110, v110
	v_fmac_f32_e32 v200, v111, v111
	v_fmac_f32_e32 v195, v112, v112
	v_fmac_f32_e32 v200, v113, v113
	v_fmac_f32_e32 v195, v114, v114
	v_fmac_f32_e32 v200, v115, v115
	v_add_f32_e32 v195, v195, v200
	v_mul_f32_e32 v196, v132, v132
	v_mul_f32_e32 v201, v133, v133
	v_fmac_f32_e32 v196, v134, v134
	v_fmac_f32_e32 v201, v135, v135
	v_fmac_f32_e32 v196, v136, v136
	v_fmac_f32_e32 v201, v137, v137
	v_fmac_f32_e32 v196, v138, v138
	v_fmac_f32_e32 v201, v139, v139
	v_fmac_f32_e32 v196, v140, v140
	v_fmac_f32_e32 v201, v141, v141
	v_fmac_f32_e32 v196, v142, v142
	v_fmac_f32_e32 v201, v143, v143
	v_fmac_f32_e32 v196, v144, v144
	v_fmac_f32_e32 v201, v145, v145
	v_fmac_f32_e32 v196, v146, v146
	v_fmac_f32_e32 v201, v147, v147
	v_add_f32_e32 v196, v196, v201
	s_nop 1
	v_add_f32_dpp v194, v194, v194 quad_perm:[1,0,3,2] row_mask:0xf bank_mask:0xf
	v_add_f32_dpp v195, v195, v195 quad_perm:[1,0,3,2] row_mask:0xf bank_mask:0xf
	v_add_f32_dpp v196, v196, v196 quad_perm:[1,0,3,2] row_mask:0xf bank_mask:0xf
	s_nop 1
	v_add_f32_dpp v194, v194, v194 quad_perm:[2,3,0,1] row_mask:0xf bank_mask:0xf
	v_add_f32_dpp v195, v195, v195 quad_perm:[2,3,0,1] row_mask:0xf bank_mask:0xf
	v_add_f32_dpp v196, v196, v196 quad_perm:[2,3,0,1] row_mask:0xf bank_mask:0xf
	s_nop 1
	v_add_f32_dpp v194, v194, v194 row_half_mirror row_mask:0xf bank_mask:0xf
	v_add_f32_dpp v195, v195, v195 row_half_mirror row_mask:0xf bank_mask:0xf
	v_add_f32_dpp v196, v196, v196 row_half_mirror row_mask:0xf bank_mask:0xf
	s_nop 1
	v_add_f32_dpp v194, v194, v194 row_mirror row_mask:0xf bank_mask:0xf
	v_add_f32_dpp v195, v195, v195 row_mirror row_mask:0xf bank_mask:0xf
	v_add_f32_dpp v196, v196, v196 row_mirror row_mask:0xf bank_mask:0xf
	s_nop 1
	v_readlane_b32 s82, v194, 0
	v_readlane_b32 s83, v194, 16
	v_readlane_b32 s84, v194, 32
	v_readlane_b32 s85, v194, 48
	s_nop 1
	v_mov_b32_e32 v202, s82
	v_add_f32_e32 v202, s83, v202
	v_add_f32_e32 v202, s84, v202
	v_add_f32_e32 v202, s85, v202
	v_readlane_b32 s82, v195, 0
	v_readlane_b32 s83, v195, 16
	v_readlane_b32 s84, v195, 32
	v_readlane_b32 s85, v195, 48
	s_nop 1
	v_mov_b32_e32 v204, s82
	v_add_f32_e32 v204, s83, v204
	v_add_f32_e32 v204, s84, v204
	v_add_f32_e32 v204, s85, v204
	v_readlane_b32 s82, v196, 0
	v_readlane_b32 s83, v196, 16
	v_readlane_b32 s84, v196, 32
	v_readlane_b32 s85, v196, 48
	s_nop 1
	v_mov_b32_e32 v206, s82
	v_add_f32_e32 v206, s83, v206
	v_add_f32_e32 v206, s84, v206
	v_add_f32_e32 v206, s85, v206
	v_fmamk_f32 v202, v202, 0x3a800000, v3
	v_fmamk_f32 v204, v204, 0x3a800000, v3
	v_fmamk_f32 v206, v206, 0x3a800000, v3
	v_rsq_f32_e32 v202, v202
	v_rsq_f32_e32 v204, v204
	v_rsq_f32_e32 v206, v206
	s_nop 1
	v_pk_mul_f32 v[68:69], v[68:69], v[202:203] op_sel_hi:[1,0]
	v_pk_mul_f32 v[70:71], v[70:71], v[202:203] op_sel_hi:[1,0]
	v_pk_mul_f32 v[72:73], v[72:73], v[202:203] op_sel_hi:[1,0]
	v_pk_mul_f32 v[74:75], v[74:75], v[202:203] op_sel_hi:[1,0]
	v_pk_mul_f32 v[76:77], v[76:77], v[202:203] op_sel_hi:[1,0]
	v_pk_mul_f32 v[78:79], v[78:79], v[202:203] op_sel_hi:[1,0]
	v_pk_mul_f32 v[80:81], v[80:81], v[202:203] op_sel_hi:[1,0]
	v_pk_mul_f32 v[82:83], v[82:83], v[202:203] op_sel_hi:[1,0]
	v_pk_fma_f32 v[68:69], v[4:5], v[68:69], v[84:85]
	v_pk_fma_f32 v[70:71], v[6:7], v[70:71], v[86:87]
	v_pk_fma_f32 v[72:73], v[8:9], v[72:73], v[88:89]
	v_pk_fma_f32 v[74:75], v[10:11], v[74:75], v[90:91]
	v_pk_fma_f32 v[76:77], v[12:13], v[76:77], v[92:93]
	v_pk_fma_f32 v[78:79], v[14:15], v[78:79], v[94:95]
	v_pk_fma_f32 v[80:81], v[16:17], v[80:81], v[96:97]
	v_pk_fma_f32 v[82:83], v[18:19], v[82:83], v[98:99]
	v_cvt_pk_bf16_f32 v164, v68, v69
	v_cvt_pk_bf16_f32 v165, v70, v71
	v_cvt_pk_bf16_f32 v166, v72, v73
	v_cvt_pk_bf16_f32 v167, v74, v75
	v_cvt_pk_bf16_f32 v168, v76, v77
	v_cvt_pk_bf16_f32 v169, v78, v79
	v_cvt_pk_bf16_f32 v170, v80, v81
	v_cvt_pk_bf16_f32 v171, v82, v83
	global_store_dwordx4 v191, v[164:167], s[70:71]
	global_store_dwordx4 v191, v[168:171], s[70:71] offset:1024
	v_pk_mul_f32 v[100:101], v[100:101], v[204:205] op_sel_hi:[1,0]
	v_pk_mul_f32 v[102:103], v[102:103], v[204:205] op_sel_hi:[1,0]
	v_pk_mul_f32 v[104:105], v[104:105], v[204:205] op_sel_hi:[1,0]
	v_pk_mul_f32 v[106:107], v[106:107], v[204:205] op_sel_hi:[1,0]
	v_pk_mul_f32 v[108:109], v[108:109], v[204:205] op_sel_hi:[1,0]
	v_pk_mul_f32 v[110:111], v[110:111], v[204:205] op_sel_hi:[1,0]
	v_pk_mul_f32 v[112:113], v[112:113], v[204:205] op_sel_hi:[1,0]
	v_pk_mul_f32 v[114:115], v[114:115], v[204:205] op_sel_hi:[1,0]
	v_pk_fma_f32 v[100:101], v[4:5], v[100:101], v[116:117]
	v_pk_fma_f32 v[102:103], v[6:7], v[102:103], v[118:119]
	v_pk_fma_f32 v[104:105], v[8:9], v[104:105], v[120:121]
	v_pk_fma_f32 v[106:107], v[10:11], v[106:107], v[122:123]
	v_pk_fma_f32 v[108:109], v[12:13], v[108:109], v[124:125]
	v_pk_fma_f32 v[110:111], v[14:15], v[110:111], v[126:127]
	v_pk_fma_f32 v[112:113], v[16:17], v[112:113], v[128:129]
	v_pk_fma_f32 v[114:115], v[18:19], v[114:115], v[130:131]
	v_cvt_pk_bf16_f32 v172, v100, v101
	v_cvt_pk_bf16_f32 v173, v102, v103
	v_cvt_pk_bf16_f32 v174, v104, v105
	v_cvt_pk_bf16_f32 v175, v106, v107
	v_cvt_pk_bf16_f32 v176, v108, v109
	v_cvt_pk_bf16_f32 v177, v110, v111
	v_cvt_pk_bf16_f32 v178, v112, v113
	v_cvt_pk_bf16_f32 v179, v114, v115
	global_store_dwordx4 v192, v[172:175], s[70:71]
	global_store_dwordx4 v192, v[176:179], s[70:71] offset:1024
	v_pk_mul_f32 v[132:133], v[132:133], v[206:207] op_sel_hi:[1,0]
	v_pk_mul_f32 v[134:135], v[134:135], v[206:207] op_sel_hi:[1,0]
	v_pk_mul_f32 v[136:137], v[136:137], v[206:207] op_sel_hi:[1,0]
	v_pk_mul_f32 v[138:139], v[138:139], v[206:207] op_sel_hi:[1,0]
	v_pk_mul_f32 v[140:141], v[140:141], v[206:207] op_sel_hi:[1,0]
	v_pk_mul_f32 v[142:143], v[142:143], v[206:207] op_sel_hi:[1,0]
	v_pk_mul_f32 v[144:145], v[144:145], v[206:207] op_sel_hi:[1,0]
	v_pk_mul_f32 v[146:147], v[146:147], v[206:207] op_sel_hi:[1,0]
	v_pk_fma_f32 v[132:133], v[4:5], v[132:133], v[148:149]
	v_pk_fma_f32 v[134:135], v[6:7], v[134:135], v[150:151]
	v_pk_fma_f32 v[136:137], v[8:9], v[136:137], v[152:153]
	v_pk_fma_f32 v[138:139], v[10:11], v[138:139], v[154:155]
	v_pk_fma_f32 v[140:141], v[12:13], v[140:141], v[156:157]
	v_pk_fma_f32 v[142:143], v[14:15], v[142:143], v[158:159]
	v_pk_fma_f32 v[144:145], v[16:17], v[144:145], v[160:161]
	v_pk_fma_f32 v[146:147], v[18:19], v[146:147], v[162:163]
	v_cvt_pk_bf16_f32 v180, v132, v133
	v_cvt_pk_bf16_f32 v181, v134, v135
	v_cvt_pk_bf16_f32 v182, v136, v137
	v_cvt_pk_bf16_f32 v183, v138, v139
	v_cvt_pk_bf16_f32 v184, v140, v141
	v_cvt_pk_bf16_f32 v185, v142, v143
	v_cvt_pk_bf16_f32 v186, v144, v145
	v_cvt_pk_bf16_f32 v187, v146, v147
	global_store_dwordx4 v193, v[180:183], s[70:71]
	global_store_dwordx4 v193, v[184:187], s[70:71] offset:1024
	s_cmp_lt_u32 s49, 0x4400
	s_cbranch_scc0 .Lrow_p12_done
	s_mov_b32 s7, s49
	s_waitcnt vmcnt(6)
	s_branch .Lrow_p12_top
.Lrow_p12_done:
.LBB0_1550:
	s_or_b64 exec, exec, s[0:1]
	s_waitcnt vmcnt(0)
	s_barrier
	s_mov_b64 s[0:1], exec
	v_readlane_b32 s6, v254, 3
	v_readlane_b32 s7, v254, 4
	s_and_b64 s[6:7], s[0:1], s[6:7]
	s_xor_b64 s[0:1], s[6:7], s[0:1]
	s_mov_b64 exec, s[6:7]
	s_cbranch_execz .LBB0_1603
	s_add_i32 s6, 0, 0x22ff0
	v_mov_b32_e32 v0, s6
	s_waitcnt vmcnt(0) expcnt(0) lgkmcnt(0)
	ds_read_b32 v2, v0
	s_add_i32 s6, 0, 0x22ff4
	v_mov_b32_e32 v0, s6
	ds_read_b32 v0, v0
	s_waitcnt lgkmcnt(1)
	v_cmp_ne_u32_e32 vcc, 0, v2
	s_cbranch_vccnz .LBB0_1566
	v_readlane_b32 s6, v254, 0
	s_mul_i32 s33, s97, s6
	s_add_u32 s6, s94, 0x32c02a00
	s_addc_u32 s7, s95, 0
	s_add_u32 s8, s94, 0x32c02c00
	s_addc_u32 s9, s95, 0
	s_add_u32 s10, s94, 0x32c02d00
	s_addc_u32 s11, s95, 0
	s_add_u32 s12, s94, 0x32c02e00
	s_addc_u32 s13, s95, 0
	s_add_u32 s14, s94, 0x32c02f00
	s_addc_u32 s15, s95, 0
	s_add_u32 s16, s94, 0x32c03000
	s_addc_u32 s17, s95, 0
	s_add_u32 s18, s94, 0x32c03100
	s_addc_u32 s19, s95, 0
	s_add_u32 s20, s94, 0x32c03200
	s_addc_u32 s21, s95, 0
	s_add_u32 s22, s94, 0x32c03300
	s_addc_u32 s23, s95, 0
	s_add_u32 s24, s94, 0x32c03400
	s_addc_u32 s25, s95, 0
	s_add_u32 s26, s94, 0x32c03500
	s_addc_u32 s27, s95, 0
	s_add_u32 s28, s94, 0x32c03600
	s_addc_u32 s29, s95, 0
	s_add_u32 s30, s94, 0x32c03700
	s_addc_u32 s31, s95, 0
	s_add_u32 s34, s94, 0x32c03800
	s_addc_u32 s35, s95, 0
	s_add_u32 s36, s94, 0x32c03900
	s_addc_u32 s37, s95, 0
	s_add_u32 s38, s94, 0x32c03a00
	s_addc_u32 s39, s95, 0
	s_add_u32 s40, s94, 0x32c03b00
	s_mul_i32 s33, s33, s96
	s_addc_u32 s41, s95, 0
	s_mov_b32 s48, 1
	v_mov_b32_e32 v16, 0
	s_branch .LBB0_1554
